# GEMM MMA blocks: the two K-halves of each accumulator issued back to back, accumulators in snake order
# speedup vs baseline: 1.0126x; 1.0126x over previous
; #define PG8_STAGE(bufoff, gbase, voff) do { _Pragma("unroll") for (int _i = 0; _i < 2; ++_i) \
;         __builtin_amdgcn_global_load_lds((const unsigned*)((const char*)(gbase) + (voff)[_i]), (LAS unsigned*)(lds + (bufoff) + ldsw + _i * 8192), 16, 0, 0); } while (0)
; #define PG8_LDA(dst, b, h) do { _Pragma("unroll") for (int m = 0; m < 4; ++m) _Pragma("unroll") for (int k = 0; k < 2; ++k) dst[m][k] = *(const LAS bf16x8*)(lds + PG8_SA(b, h) + aoff + m * 2048 + k * 1024); } while (0)
; #define PG8_LDB(dst, b, h) do { _Pragma("unroll") for (int n = 0; n < 2; ++n) _Pragma("unroll") for (int k = 0; k < 2; ++k) dst[n][k] = *(const LAS bf16x8*)(lds + PG8_SB(b, h) + boff + n * 2048 + k * 1024); } while (0)
; #define PG8_MMA(ai, bj, At, Bt) do { __builtin_amdgcn_s_setprio(1); _Pragma("unroll") for (int m = 0; m < 4; ++m) _Pragma("unroll") for (int n = 0; n < 2; ++n) _Pragma("unroll") for (int k = 0; k < 2; ++k) \
;         acc[ai][bj][m][n] = __builtin_amdgcn_mfma_f32_16x16x32_bf16(Bt[n][k], At[m][k], acc[ai][bj][m][n], 0, 0, 0); __builtin_amdgcn_s_setprio(0); } while (0)
; #define PG8_WAIT_L(n) asm volatile("s_waitcnt lgkmcnt(" #n ")" ::: "memory")
; #define PG8_BAR __builtin_amdgcn_s_barrier()
; #define PG8_SCHED __builtin_amdgcn_sched_barrier(0)
; template <class Epi, class Ptrs>
; __device__ __forceinline__ void gemm_phase(LAS unsigned char* lds, const int K, const StaticOrder& S, const Ptrs& P, const Epi& E) {
;     ...
;             PG8_LDB(B0, 0, 0); PG8_SCHED; PG8_LDA(At, 0, 0); PG8_STAGE(PG8_SA(1, 1), a1 + hstep, voffA);
;             PG8_WAIT_L(8); PG8_BAR; PG8_WAIT_L(0); PG8_MMA(0, 0, At, B0); PG8_BAR; PG8_SCHED;
;             PG8_LDB(B1, 0, 1); PG8_STAGE(PG8_SB(0, 0), b2, voffB);
;             PG8_BAR; PG8_WAIT_L(0); PG8_MMA(0, 1, At, B1); PG8_BAR;
;             PG8_LDA(At, 0, 1); PG8_STAGE(PG8_SA(0, 0), a2, voffA);
;             PG8_BAR; PG8_WAIT_L(0); PG8_MMA(1, 0, At, B0); PG8_BAR; PG8_SCHED;
.LBB0_127:
	ds_read_b128 v[150:153], v205
	ds_read_b128 v[154:157], v205 offset:1024
	ds_read_b128 v[158:161], v205 offset:2048
	ds_read_b128 v[162:165], v205 offset:3072
	s_add_u32 s69, s6, 0xfffc0080
	s_addc_u32 s71, s7, -1
	s_cmp_eq_u32 s63, 12
	s_cselect_b32 s81, s1, s71
	s_cselect_b32 s80, s0, s69
	s_cselect_b32 s79, s73, s25
	s_cselect_b32 s78, s72, s20
	v_lshl_add_u64 v[198:199], s[6:7], 0, v[142:143]
	s_add_i32 m0, s67, 0xc000
	ds_read_b128 v[166:169], v206
	ds_read_b128 v[170:173], v206 offset:1024
	ds_read_b128 v[174:177], v206 offset:2048
	ds_read_b128 v[178:181], v206 offset:3072
	ds_read_b128 v[182:185], v206 offset:4096
	ds_read_b128 v[186:189], v206 offset:5120
	ds_read_b128 v[190:193], v206 offset:6144
	ds_read_b128 v[194:197], v206 offset:7168
	global_load_lds_dwordx4 v[198:199], off
	v_lshl_add_u64 v[198:199], s[6:7], 0, v[144:145]
	s_add_i32 m0, s67, 0xe000
	s_nop 0
	global_load_lds_dwordx4 v[198:199], off
	s_waitcnt lgkmcnt(8)
	s_barrier
	s_waitcnt lgkmcnt(0)
	s_setprio 1
	s_waitcnt lgkmcnt(0)
	v_mfma_f32_16x16x32_bf16 v[120:123], v[150:153], v[166:169], v[120:123]
	v_mfma_f32_16x16x32_bf16 v[120:123], v[154:157], v[170:173], v[120:123]
	v_mfma_f32_16x16x32_bf16 v[116:119], v[162:165], v[170:173], v[116:119]
	v_mfma_f32_16x16x32_bf16 v[116:119], v[158:161], v[166:169], v[116:119]
	v_mfma_f32_16x16x32_bf16 v[100:103], v[158:161], v[174:177], v[100:103]
	v_mfma_f32_16x16x32_bf16 v[100:103], v[162:165], v[178:181], v[100:103]
	v_mfma_f32_16x16x32_bf16 v[104:107], v[154:157], v[178:181], v[104:107]
	v_mfma_f32_16x16x32_bf16 v[104:107], v[150:153], v[174:177], v[104:107]
	v_mfma_f32_16x16x32_bf16 v[88:91], v[150:153], v[182:185], v[88:91]
	v_mfma_f32_16x16x32_bf16 v[88:91], v[154:157], v[186:189], v[88:91]
	v_mfma_f32_16x16x32_bf16 v[84:87], v[162:165], v[186:189], v[84:87]
	v_mfma_f32_16x16x32_bf16 v[84:87], v[158:161], v[182:185], v[84:87]
	v_mfma_f32_16x16x32_bf16 v[68:71], v[158:161], v[190:193], v[68:71]
	v_mfma_f32_16x16x32_bf16 v[68:71], v[162:165], v[194:197], v[68:71]
	v_mfma_f32_16x16x32_bf16 v[72:75], v[154:157], v[194:197], v[72:75]
	v_mfma_f32_16x16x32_bf16 v[72:75], v[150:153], v[190:193], v[72:75]
	s_setprio 0
	s_barrier
	s_add_i32 s69, s91, s65
	v_lshl_add_u64 v[202:203], s[78:79], 0, v[134:135]
	s_mov_b32 m0, s69
	ds_read_b128 v[198:201], v207
	ds_read_b128 v[210:213], v207 offset:1024
	ds_read_b128 v[214:217], v207 offset:2048
	ds_read_b128 v[218:221], v207 offset:3072
	global_load_lds_dwordx4 v[202:203], off
	v_lshl_add_u64 v[222:223], s[78:79], 0, v[138:139]
	s_add_i32 m0, s69, 0x2000
	s_nop 0
	global_load_lds_dwordx4 v[222:223], off
	s_barrier
	s_waitcnt lgkmcnt(0)
	s_setprio 1
	s_waitcnt lgkmcnt(0)
	v_mfma_f32_16x16x32_bf16 v[124:127], v[198:201], v[166:169], v[124:127]
	v_mfma_f32_16x16x32_bf16 v[124:127], v[210:213], v[170:173], v[124:127]
	v_mfma_f32_16x16x32_bf16 v[112:115], v[218:221], v[170:173], v[112:115]
	v_mfma_f32_16x16x32_bf16 v[112:115], v[214:217], v[166:169], v[112:115]
	v_mfma_f32_16x16x32_bf16 v[96:99], v[214:217], v[174:177], v[96:99]
	v_mfma_f32_16x16x32_bf16 v[96:99], v[218:221], v[178:181], v[96:99]
	v_mfma_f32_16x16x32_bf16 v[108:111], v[210:213], v[178:181], v[108:111]
	v_mfma_f32_16x16x32_bf16 v[108:111], v[198:201], v[174:177], v[108:111]
	v_mfma_f32_16x16x32_bf16 v[92:95], v[198:201], v[182:185], v[92:95]
	v_mfma_f32_16x16x32_bf16 v[92:95], v[210:213], v[186:189], v[92:95]
	v_mfma_f32_16x16x32_bf16 v[80:83], v[218:221], v[186:189], v[80:83]
	v_mfma_f32_16x16x32_bf16 v[80:83], v[214:217], v[182:185], v[80:83]
	v_mfma_f32_16x16x32_bf16 v[64:67], v[214:217], v[190:193], v[64:67]
	v_mfma_f32_16x16x32_bf16 v[64:67], v[218:221], v[194:197], v[64:67]
	v_mfma_f32_16x16x32_bf16 v[76:79], v[210:213], v[194:197], v[76:79]
	v_mfma_f32_16x16x32_bf16 v[76:79], v[198:201], v[190:193], v[76:79]
	s_setprio 0
	s_mov_b32 m0, s67
	v_lshl_add_u64 v[224:225], s[80:81], 0, v[132:133]
	s_barrier
	ds_read_b128 v[166:169], v206 offset:16384
	ds_read_b128 v[170:173], v206 offset:17408
	ds_read_b128 v[174:177], v206 offset:18432
	ds_read_b128 v[178:181], v206 offset:19456
	ds_read_b128 v[182:185], v206 offset:20480
	ds_read_b128 v[186:189], v206 offset:21504
	ds_read_b128 v[190:193], v206 offset:22528
	ds_read_b128 v[194:197], v206 offset:23552
	global_load_lds_dwordx4 v[224:225], off
	v_lshl_add_u64 v[226:227], s[80:81], 0, v[136:137]
	s_mov_b32 m0, s75
	s_nop 0
	global_load_lds_dwordx4 v[226:227], off
	s_barrier
	s_waitcnt lgkmcnt(0)
	s_setprio 1
	s_waitcnt lgkmcnt(0)
	v_mfma_f32_16x16x32_bf16 v[56:59], v[150:153], v[166:169], v[56:59]
	v_mfma_f32_16x16x32_bf16 v[56:59], v[154:157], v[170:173], v[56:59]
	v_mfma_f32_16x16x32_bf16 v[52:55], v[162:165], v[170:173], v[52:55]
	v_mfma_f32_16x16x32_bf16 v[52:55], v[158:161], v[166:169], v[52:55]
	v_mfma_f32_16x16x32_bf16 v[36:39], v[158:161], v[174:177], v[36:39]
	v_mfma_f32_16x16x32_bf16 v[36:39], v[162:165], v[178:181], v[36:39]
	v_mfma_f32_16x16x32_bf16 v[40:43], v[154:157], v[178:181], v[40:43]
	v_mfma_f32_16x16x32_bf16 v[40:43], v[150:153], v[174:177], v[40:43]
	v_mfma_f32_16x16x32_bf16 v[24:27], v[150:153], v[182:185], v[24:27]
	v_mfma_f32_16x16x32_bf16 v[24:27], v[154:157], v[186:189], v[24:27]
	v_mfma_f32_16x16x32_bf16 v[20:23], v[162:165], v[186:189], v[20:23]
	v_mfma_f32_16x16x32_bf16 v[20:23], v[158:161], v[182:185], v[20:23]
	v_mfma_f32_16x16x32_bf16 v[4:7], v[158:161], v[190:193], v[4:7]
	v_mfma_f32_16x16x32_bf16 v[4:7], v[162:165], v[194:197], v[4:7]
	v_mfma_f32_16x16x32_bf16 v[8:11], v[154:157], v[194:197], v[8:11]
	v_mfma_f32_16x16x32_bf16 v[8:11], v[150:153], v[190:193], v[8:11]
	s_setprio 0
	s_barrier
; #define PG8_STAGE(bufoff, gbase, voff) do { _Pragma("unroll") for (int _i = 0; _i < 2; ++_i) \
;         __builtin_amdgcn_global_load_lds((const unsigned*)((const char*)(gbase) + (voff)[_i]), (LAS unsigned*)(lds + (bufoff) + ldsw + _i * 8192), 16, 0, 0); } while (0)
; #define PG8_LDA(dst, b, h) do { _Pragma("unroll") for (int m = 0; m < 4; ++m) _Pragma("unroll") for (int k = 0; k < 2; ++k) dst[m][k] = *(const LAS bf16x8*)(lds + PG8_SA(b, h) + aoff + m * 2048 + k * 1024); } while (0)
; #define PG8_LDB(dst, b, h) do { _Pragma("unroll") for (int n = 0; n < 2; ++n) _Pragma("unroll") for (int k = 0; k < 2; ++k) dst[n][k] = *(const LAS bf16x8*)(lds + PG8_SB(b, h) + boff + n * 2048 + k * 1024); } while (0)
; #define PG8_MMA(ai, bj, At, Bt) do { __builtin_amdgcn_s_setprio(1); _Pragma("unroll") for (int m = 0; m < 4; ++m) _Pragma("unroll") for (int n = 0; n < 2; ++n) _Pragma("unroll") for (int k = 0; k < 2; ++k) \
;         acc[ai][bj][m][n] = __builtin_amdgcn_mfma_f32_16x16x32_bf16(Bt[n][k], At[m][k], acc[ai][bj][m][n], 0, 0, 0); __builtin_amdgcn_s_setprio(0); } while (0)
; #define PG8_WAIT_V(n) asm volatile("s_waitcnt vmcnt(" #n ")" ::: "memory")
; #define PG8_WAIT_L(n) asm volatile("s_waitcnt lgkmcnt(" #n ")" ::: "memory")
; #define PG8_BAR __builtin_amdgcn_s_barrier()
; #define PG8_SCHED __builtin_amdgcn_sched_barrier(0)
; template <class Epi, class Ptrs>
; __device__ __forceinline__ void gemm_phase(LAS unsigned char* lds, const int K, const StaticOrder& S, const Ptrs& P, const Epi& E) {
;     ...
;             PG8_STAGE(PG8_SB(0, 1), b2 + hstep, voffB);
;             PG8_WAIT_V(6); PG8_BAR; PG8_MMA(1, 1, At, B1); PG8_BAR;
;             PG8_LDB(B0, 1, 0); PG8_SCHED; PG8_LDA(At, 1, 0); PG8_STAGE(PG8_SA(0, 1), a2 + hstep, voffA);
;             PG8_WAIT_L(8); PG8_BAR; PG8_WAIT_L(0); PG8_MMA(0, 0, At, B0); PG8_BAR; PG8_SCHED;
;             PG8_LDB(B1, 1, 1); PG8_STAGE(PG8_SB(1, 0), b3, voffB);
;             PG8_BAR; PG8_WAIT_L(0); PG8_MMA(0, 1, At, B1); PG8_BAR;
	s_add_u32 s82, s78, 0x40000
	s_addc_u32 s83, s79, 0
	s_add_i32 s69, s92, s65
	v_lshl_add_u64 v[150:151], s[82:83], 0, v[134:135]
	s_mov_b32 m0, s69
	s_nop 0
	global_load_lds_dwordx4 v[150:151], off
	v_lshl_add_u64 v[150:151], s[82:83], 0, v[138:139]
	s_add_i32 m0, s69, 0x2000
	s_nop 0
	global_load_lds_dwordx4 v[150:151], off
	s_waitcnt vmcnt(6)
	s_barrier
	s_setprio 1
	v_mfma_f32_16x16x32_bf16 v[60:63], v[198:201], v[166:169], v[60:63]
	v_mfma_f32_16x16x32_bf16 v[60:63], v[210:213], v[170:173], v[60:63]
	v_mfma_f32_16x16x32_bf16 v[48:51], v[218:221], v[170:173], v[48:51]
	v_mfma_f32_16x16x32_bf16 v[48:51], v[214:217], v[166:169], v[48:51]
	v_mfma_f32_16x16x32_bf16 v[32:35], v[214:217], v[174:177], v[32:35]
	v_mfma_f32_16x16x32_bf16 v[32:35], v[218:221], v[178:181], v[32:35]
	v_mfma_f32_16x16x32_bf16 v[44:47], v[210:213], v[178:181], v[44:47]
	v_mfma_f32_16x16x32_bf16 v[44:47], v[198:201], v[174:177], v[44:47]
	v_mfma_f32_16x16x32_bf16 v[28:31], v[198:201], v[182:185], v[28:31]
	v_mfma_f32_16x16x32_bf16 v[28:31], v[210:213], v[186:189], v[28:31]
	v_mfma_f32_16x16x32_bf16 v[16:19], v[218:221], v[186:189], v[16:19]
	v_mfma_f32_16x16x32_bf16 v[16:19], v[214:217], v[182:185], v[16:19]
	v_mfma_f32_16x16x32_bf16 v[0:3], v[214:217], v[190:193], v[0:3]
	v_mfma_f32_16x16x32_bf16 v[0:3], v[218:221], v[194:197], v[0:3]
	v_mfma_f32_16x16x32_bf16 v[12:15], v[210:213], v[194:197], v[12:15]
	v_mfma_f32_16x16x32_bf16 v[12:15], v[198:201], v[190:193], v[12:15]
	s_setprio 0
	s_add_i32 s69, 0, 0x18000
	v_add_u32_e32 v140, s69, v131
	s_barrier
	ds_read_b128 v[150:153], v140
	ds_read_b128 v[154:157], v140 offset:1024
	ds_read_b128 v[158:161], v140 offset:2048
	ds_read_b128 v[162:165], v140 offset:3072
	s_add_u32 s80, s80, 0x40000
	s_addc_u32 s81, s81, 0
	s_mov_b32 m0, s77
	v_lshl_add_u64 v[198:199], s[80:81], 0, v[132:133]
	ds_read_b128 v[166:169], v206 offset:32768
	ds_read_b128 v[170:173], v206 offset:33792
	ds_read_b128 v[174:177], v206 offset:34816
	ds_read_b128 v[178:181], v206 offset:35840
	ds_read_b128 v[182:185], v206 offset:36864
	ds_read_b128 v[186:189], v206 offset:37888
	ds_read_b128 v[190:193], v206 offset:38912
	ds_read_b128 v[194:197], v206 offset:39936
	global_load_lds_dwordx4 v[198:199], off
	v_lshl_add_u64 v[198:199], s[80:81], 0, v[136:137]
	s_mov_b32 m0, s85
	s_nop 0
	global_load_lds_dwordx4 v[198:199], off
	s_waitcnt lgkmcnt(8)
	s_barrier
	s_waitcnt lgkmcnt(0)
	s_setprio 1
	s_waitcnt lgkmcnt(0)
	v_mfma_f32_16x16x32_bf16 v[120:123], v[150:153], v[166:169], v[120:123]
	v_mfma_f32_16x16x32_bf16 v[120:123], v[154:157], v[170:173], v[120:123]
	v_mfma_f32_16x16x32_bf16 v[116:119], v[162:165], v[170:173], v[116:119]
	v_mfma_f32_16x16x32_bf16 v[116:119], v[158:161], v[166:169], v[116:119]
	v_mfma_f32_16x16x32_bf16 v[100:103], v[158:161], v[174:177], v[100:103]
	v_mfma_f32_16x16x32_bf16 v[100:103], v[162:165], v[178:181], v[100:103]
	v_mfma_f32_16x16x32_bf16 v[104:107], v[154:157], v[178:181], v[104:107]
	v_mfma_f32_16x16x32_bf16 v[104:107], v[150:153], v[174:177], v[104:107]
	v_mfma_f32_16x16x32_bf16 v[88:91], v[150:153], v[182:185], v[88:91]
	v_mfma_f32_16x16x32_bf16 v[88:91], v[154:157], v[186:189], v[88:91]
	v_mfma_f32_16x16x32_bf16 v[84:87], v[162:165], v[186:189], v[84:87]
	v_mfma_f32_16x16x32_bf16 v[84:87], v[158:161], v[182:185], v[84:87]
	v_mfma_f32_16x16x32_bf16 v[68:71], v[158:161], v[190:193], v[68:71]
	v_mfma_f32_16x16x32_bf16 v[68:71], v[162:165], v[194:197], v[68:71]
	v_mfma_f32_16x16x32_bf16 v[72:75], v[154:157], v[194:197], v[72:75]
	v_mfma_f32_16x16x32_bf16 v[72:75], v[150:153], v[190:193], v[72:75]
	s_setprio 0
	s_barrier
	s_add_i32 s71, 0, 0x1c000
	s_add_i32 s69, s69, s65
	v_add_u32_e32 v140, s71, v131
	v_lshl_add_u64 v[202:203], v[202:203], 0, s[58:59]
	s_mov_b32 m0, s69
	ds_read_b128 v[198:201], v140
	ds_read_b128 v[210:213], v140 offset:1024
	ds_read_b128 v[214:217], v140 offset:2048
	ds_read_b128 v[218:221], v140 offset:3072
	global_load_lds_dwordx4 v[202:203], off
	v_lshl_add_u64 v[202:203], v[222:223], 0, s[58:59]
	s_add_i32 m0, s69, 0x2000
	s_nop 0
	global_load_lds_dwordx4 v[202:203], off
	s_barrier
; #define PG8_WAIT_V(n) asm volatile("s_waitcnt vmcnt(" #n ")" ::: "memory")
; template <class Epi, class Ptrs>
; __device__ __forceinline__ void gemm_phase(LAS unsigned char* lds, const int K, const StaticOrder& S, const Ptrs& P, const Epi& E) {
;     ...
;             PG8_BAR; PG8_WAIT_L(0); PG8_MMA(0, 1, At, B1); PG8_BAR;
;             PG8_LDA(At, 1, 1); PG8_STAGE(PG8_SA(1, 0), a3, voffA);
;             PG8_BAR; PG8_WAIT_L(0); PG8_MMA(1, 0, At, B0); PG8_BAR; PG8_SCHED;
;             PG8_STAGE(PG8_SB(1, 1), b3 + hstep, voffB);
;             PG8_WAIT_V(6); PG8_BAR; PG8_MMA(1, 1, At, B1); PG8_BAR;
;     __device__ __forceinline__ void operator()(const f32x4 (&acc)[2][2][4][2], const Unit& u, int ui, int wr, int wc, int fr, int fq) const {
;     ...
;         if (pn < 8) {
;             bf16_t* base = (bf16_t*)(ws + WS_U) + (size_t)(u.pm * 256 + wr * 64 + fr) * DM + pn * 128 + wc * 32 + 8 * fq;
; #pragma unroll
;             for (int ai = 0; ai < 2; ++ai)
; #pragma unroll
;                 for (int m = 0; m < 4; ++m) {
;                     const f32x4 g0 = g1_4(acc[ai][0][m][0], acc[ai][1][m][0]), g1 = g1_4(acc[ai][0][m][1], acc[ai][1][m][1]);
;                     *(u32x4*)(base + (size_t)(ai * 128 + m * 16) * DM) = pack8(g0, g1); }
;             return; }
;         if (pn >= 17 && pn < 21) {
;             bf16_t* base = (bf16_t*)(dout + DO_GVT) + (size_t)((pn - 17) * 256 + wr * 64 + fr) * MTOK + u.pm * 256 + wc * 32 + 8 * fq;
;             float* pp = (float*)(ws + WS_PART) + (size_t)(u.pm * 256 + wc * 32 + 8 * fq) * 8 + (pn - 17) * 2 + wr;
; #pragma unroll
;             for (int bj = 0; bj < 2; ++bj) { f32x4 sq0 = {0.f, 0.f, 0.f, 0.f}, sq1 = {0.f, 0.f, 0.f, 0.f};
; #pragma unroll
;                 for (int ai = 0; ai < 2; ++ai)
; #pragma unroll
;                     for (int m = 0; m < 4; ++m) { const f32x4 g0 = gelu4(acc[ai][bj][m][0]), g1 = gelu4(acc[ai][bj][m][1]);
;                         sq0 += g0 * g0; sq1 += g1 * g1;
;                         *(u32x4*)(base + (size_t)(ai * 128 + m * 16) * MTOK + bj * 128) = pack8(g0, g1); }
; #pragma unroll
;                 for (int j = 0; j < 4; ++j) { const float t0 = row16_sum(sq0[j]), t1 = row16_sum(sq1[j]); if (fr == 0) { pp[(size_t)(bj * 128 + j) * 8] = t0; pp[(size_t)(bj * 128 + 4 + j) * 8] = t1; } } }
;             return; }
;         bf16_t* base; size_t ld; int row0, col0, act;
	s_waitcnt lgkmcnt(0)
	s_setprio 1
	s_waitcnt lgkmcnt(0)
	v_mfma_f32_16x16x32_bf16 v[124:127], v[198:201], v[166:169], v[124:127]
	v_mfma_f32_16x16x32_bf16 v[124:127], v[210:213], v[170:173], v[124:127]
	v_mfma_f32_16x16x32_bf16 v[112:115], v[218:221], v[170:173], v[112:115]
	v_mfma_f32_16x16x32_bf16 v[112:115], v[214:217], v[166:169], v[112:115]
	v_mfma_f32_16x16x32_bf16 v[96:99], v[214:217], v[174:177], v[96:99]
	v_mfma_f32_16x16x32_bf16 v[96:99], v[218:221], v[178:181], v[96:99]
	v_mfma_f32_16x16x32_bf16 v[108:111], v[210:213], v[178:181], v[108:111]
	v_mfma_f32_16x16x32_bf16 v[108:111], v[198:201], v[174:177], v[108:111]
	v_mfma_f32_16x16x32_bf16 v[92:95], v[198:201], v[182:185], v[92:95]
	v_mfma_f32_16x16x32_bf16 v[92:95], v[210:213], v[186:189], v[92:95]
	v_mfma_f32_16x16x32_bf16 v[80:83], v[218:221], v[186:189], v[80:83]
	v_mfma_f32_16x16x32_bf16 v[80:83], v[214:217], v[182:185], v[80:83]
	v_mfma_f32_16x16x32_bf16 v[64:67], v[214:217], v[190:193], v[64:67]
	v_mfma_f32_16x16x32_bf16 v[64:67], v[218:221], v[194:197], v[64:67]
	v_mfma_f32_16x16x32_bf16 v[76:79], v[210:213], v[194:197], v[76:79]
	v_mfma_f32_16x16x32_bf16 v[76:79], v[198:201], v[190:193], v[76:79]
	s_setprio 0
	s_mov_b32 m0, s89
	v_lshl_add_u64 v[202:203], v[224:225], 0, s[58:59]
	s_barrier
	ds_read_b128 v[166:169], v206 offset:49152
	ds_read_b128 v[170:173], v206 offset:50176
	ds_read_b128 v[174:177], v206 offset:51200
	ds_read_b128 v[178:181], v206 offset:52224
	ds_read_b128 v[182:185], v206 offset:53248
	ds_read_b128 v[186:189], v206 offset:54272
	ds_read_b128 v[190:193], v206 offset:55296
	ds_read_b128 v[194:197], v206 offset:56320
	global_load_lds_dwordx4 v[202:203], off
	v_lshl_add_u64 v[202:203], v[226:227], 0, s[58:59]
	s_mov_b32 m0, s90
	s_nop 0
	global_load_lds_dwordx4 v[202:203], off
	s_barrier
	s_waitcnt lgkmcnt(0)
	s_setprio 1
	s_waitcnt lgkmcnt(0)
	v_mfma_f32_16x16x32_bf16 v[56:59], v[150:153], v[166:169], v[56:59]
	v_mfma_f32_16x16x32_bf16 v[56:59], v[154:157], v[170:173], v[56:59]
	v_mfma_f32_16x16x32_bf16 v[52:55], v[162:165], v[170:173], v[52:55]
	v_mfma_f32_16x16x32_bf16 v[52:55], v[158:161], v[166:169], v[52:55]
	v_mfma_f32_16x16x32_bf16 v[36:39], v[158:161], v[174:177], v[36:39]
	v_mfma_f32_16x16x32_bf16 v[36:39], v[162:165], v[178:181], v[36:39]
	v_mfma_f32_16x16x32_bf16 v[40:43], v[154:157], v[178:181], v[40:43]
	v_mfma_f32_16x16x32_bf16 v[40:43], v[150:153], v[174:177], v[40:43]
	v_mfma_f32_16x16x32_bf16 v[24:27], v[150:153], v[182:185], v[24:27]
	v_mfma_f32_16x16x32_bf16 v[24:27], v[154:157], v[186:189], v[24:27]
	v_mfma_f32_16x16x32_bf16 v[20:23], v[162:165], v[186:189], v[20:23]
	v_mfma_f32_16x16x32_bf16 v[20:23], v[158:161], v[182:185], v[20:23]
	v_mfma_f32_16x16x32_bf16 v[4:7], v[158:161], v[190:193], v[4:7]
	v_mfma_f32_16x16x32_bf16 v[4:7], v[162:165], v[194:197], v[4:7]
	v_mfma_f32_16x16x32_bf16 v[8:11], v[154:157], v[194:197], v[8:11]
	v_mfma_f32_16x16x32_bf16 v[8:11], v[150:153], v[190:193], v[8:11]
	s_setprio 0
	s_barrier
	s_add_u32 s78, s78, 0x40080
	s_addc_u32 s79, s79, 0
	s_add_i32 s69, s71, s65
	v_lshl_add_u64 v[150:151], s[78:79], 0, v[134:135]
	s_mov_b32 m0, s69
	s_nop 0
	global_load_lds_dwordx4 v[150:151], off
	v_lshl_add_u64 v[150:151], s[78:79], 0, v[138:139]
	s_add_i32 m0, s69, 0x2000
	s_nop 0
	global_load_lds_dwordx4 v[150:151], off
	s_waitcnt vmcnt(6)
	s_barrier
	s_setprio 1
	v_mfma_f32_16x16x32_bf16 v[60:63], v[198:201], v[166:169], v[60:63]
	v_mfma_f32_16x16x32_bf16 v[60:63], v[210:213], v[170:173], v[60:63]
	v_mfma_f32_16x16x32_bf16 v[48:51], v[218:221], v[170:173], v[48:51]
	v_mfma_f32_16x16x32_bf16 v[48:51], v[214:217], v[166:169], v[48:51]
	v_mfma_f32_16x16x32_bf16 v[32:35], v[214:217], v[174:177], v[32:35]
	v_mfma_f32_16x16x32_bf16 v[32:35], v[218:221], v[178:181], v[32:35]
	v_mfma_f32_16x16x32_bf16 v[44:47], v[210:213], v[178:181], v[44:47]
	v_mfma_f32_16x16x32_bf16 v[44:47], v[198:201], v[174:177], v[44:47]
	v_mfma_f32_16x16x32_bf16 v[28:31], v[198:201], v[182:185], v[28:31]
	v_mfma_f32_16x16x32_bf16 v[28:31], v[210:213], v[186:189], v[28:31]
	v_mfma_f32_16x16x32_bf16 v[16:19], v[218:221], v[186:189], v[16:19]
	v_mfma_f32_16x16x32_bf16 v[16:19], v[214:217], v[182:185], v[16:19]
	v_mfma_f32_16x16x32_bf16 v[0:3], v[214:217], v[190:193], v[0:3]
	v_mfma_f32_16x16x32_bf16 v[0:3], v[218:221], v[194:197], v[0:3]
	v_mfma_f32_16x16x32_bf16 v[12:15], v[210:213], v[194:197], v[12:15]
	v_mfma_f32_16x16x32_bf16 v[12:15], v[198:201], v[190:193], v[12:15]
	s_setprio 0
	s_add_i32 s63, s63, 2
	s_add_u32 s6, s6, 0x100
	s_addc_u32 s7, s7, 0
	s_add_u32 s20, s20, 0x100
	s_addc_u32 s25, s25, 0
	s_cmp_gt_u32 s63, 13
	s_barrier
	s_cbranch_scc0 .LBB0_127
	s_cmp_gt_i32 s74, 7
	s_mov_b64 s[6:7], -1
	s_cbranch_scc0 .LBB0_188
	s_sub_i32 s25, s74, 17
	s_cmp_gt_u32 s25, 3
	s_cbranch_scc0 .LBB0_170
	s_lshl_b32 s69, s76, 8
	s_cmp_gt_u32 s74, 11
	s_cbranch_scc0 .LBB0_135
	s_cmp_eq_u32 s74, 12
	s_mov_b64 s[6:7], 0
	s_cbranch_scc1 .LBB0_134
	s_cmp_gt_u32 s74, 16
	s_cbranch_scc1 .LBB0_191
	s_lshl_b32 s20, s74, 8
	v_readlane_b32 s80, v254, 2
	s_addk_i32 s20, 0xf300
	s_mov_b64 s[78:79], 0x400
	s_mov_b64 s[82:83], -1
	s_mov_b32 s63, s69
	v_readlane_b32 s81, v254, 3
	s_andn2_b64 vcc, exec, s[6:7]
	s_cbranch_vccz .LBB0_136
	s_branch .LBB0_137

; #define PG8_STAGE(bufoff, gbase, voff) do { _Pragma("unroll") for (int _i = 0; _i < 2; ++_i) \
;         __builtin_amdgcn_global_load_lds((const unsigned*)((const char*)(gbase) + (voff)[_i]), (LAS unsigned*)(lds + (bufoff) + ldsw + _i * 8192), 16, 0, 0); } while (0)
; #define PG8_LDA(dst, b, h) do { _Pragma("unroll") for (int m = 0; m < 4; ++m) _Pragma("unroll") for (int k = 0; k < 2; ++k) dst[m][k] = *(const LAS bf16x8*)(lds + PG8_SA(b, h) + aoff + m * 2048 + k * 1024); } while (0)
; #define PG8_LDB(dst, b, h) do { _Pragma("unroll") for (int n = 0; n < 2; ++n) _Pragma("unroll") for (int k = 0; k < 2; ++k) dst[n][k] = *(const LAS bf16x8*)(lds + PG8_SB(b, h) + boff + n * 2048 + k * 1024); } while (0)
; #define PG8_MMA(ai, bj, At, Bt) do { __builtin_amdgcn_s_setprio(1); _Pragma("unroll") for (int m = 0; m < 4; ++m) _Pragma("unroll") for (int n = 0; n < 2; ++n) _Pragma("unroll") for (int k = 0; k < 2; ++k) \
;         acc[ai][bj][m][n] = __builtin_amdgcn_mfma_f32_16x16x32_bf16(Bt[n][k], At[m][k], acc[ai][bj][m][n], 0, 0, 0); __builtin_amdgcn_s_setprio(0); } while (0)
; #define PG8_WAIT_L(n) asm volatile("s_waitcnt lgkmcnt(" #n ")" ::: "memory")
; #define PG8_BAR __builtin_amdgcn_s_barrier()
; #define PG8_SCHED __builtin_amdgcn_sched_barrier(0)
; template <class Epi, class Ptrs>
; __device__ __forceinline__ void gemm_phase(LAS unsigned char* lds, const int K, const StaticOrder& S, const Ptrs& P, const Epi& E) {
;     ...
;             PG8_LDB(B0, 0, 0); PG8_SCHED; PG8_LDA(At, 0, 0); PG8_STAGE(PG8_SA(1, 1), a1 + hstep, voffA);
;             PG8_WAIT_L(8); PG8_BAR; PG8_WAIT_L(0); PG8_MMA(0, 0, At, B0); PG8_BAR; PG8_SCHED;
;             PG8_LDB(B1, 0, 1); PG8_STAGE(PG8_SB(0, 0), b2, voffB);
;             PG8_BAR; PG8_WAIT_L(0); PG8_MMA(0, 1, At, B1); PG8_BAR;
;             PG8_LDA(At, 0, 1); PG8_STAGE(PG8_SA(0, 0), a2, voffA);
;             PG8_BAR; PG8_WAIT_L(0); PG8_MMA(1, 0, At, B0); PG8_BAR; PG8_SCHED;
.LBB0_353:
	ds_read_b128 v[128:131], v207
	ds_read_b128 v[132:135], v207 offset:1024
	ds_read_b128 v[136:139], v207 offset:2048
	ds_read_b128 v[140:143], v207 offset:3072
	s_add_u32 s42, s38, 0xfffc0080
	s_addc_u32 s43, s39, -1
	s_cmp_eq_u32 s41, 12
	s_cselect_b32 s45, s1, s43
	s_cselect_b32 s44, s0, s42
	s_cselect_b32 s43, s25, s23
	s_cselect_b32 s42, s24, s21
	v_lshl_add_u64 v[192:193], s[38:39], 0, v[184:185]
	s_add_i32 m0, s54, 0xc000
	ds_read_b128 v[144:147], v209
	ds_read_b128 v[148:151], v209 offset:1024
	ds_read_b128 v[152:155], v209 offset:2048
	ds_read_b128 v[156:159], v209 offset:3072
	ds_read_b128 v[160:163], v209 offset:4096
	ds_read_b128 v[164:167], v209 offset:5120
	ds_read_b128 v[168:171], v209 offset:6144
	ds_read_b128 v[172:175], v209 offset:7168
	global_load_lds_dwordx4 v[192:193], off
	v_lshl_add_u64 v[192:193], s[38:39], 0, v[186:187]
	s_add_i32 m0, s54, 0xe000
	s_nop 0
	global_load_lds_dwordx4 v[192:193], off
	s_waitcnt lgkmcnt(8)
	s_barrier
	s_waitcnt lgkmcnt(0)
	s_setprio 1
	s_waitcnt lgkmcnt(0)
	v_mfma_f32_16x16x32_bf16 v[124:127], v[128:131], v[144:147], v[124:127]
	v_mfma_f32_16x16x32_bf16 v[124:127], v[132:135], v[148:151], v[124:127]
	v_mfma_f32_16x16x32_bf16 v[120:123], v[140:143], v[148:151], v[120:123]
	v_mfma_f32_16x16x32_bf16 v[120:123], v[136:139], v[144:147], v[120:123]
	v_mfma_f32_16x16x32_bf16 v[104:107], v[136:139], v[152:155], v[104:107]
	v_mfma_f32_16x16x32_bf16 v[104:107], v[140:143], v[156:159], v[104:107]
	v_mfma_f32_16x16x32_bf16 v[108:111], v[132:135], v[156:159], v[108:111]
	v_mfma_f32_16x16x32_bf16 v[108:111], v[128:131], v[152:155], v[108:111]
	v_mfma_f32_16x16x32_bf16 v[92:95], v[128:131], v[160:163], v[92:95]
	v_mfma_f32_16x16x32_bf16 v[92:95], v[132:135], v[164:167], v[92:95]
	v_mfma_f32_16x16x32_bf16 v[88:91], v[140:143], v[164:167], v[88:91]
	v_mfma_f32_16x16x32_bf16 v[88:91], v[136:139], v[160:163], v[88:91]
	v_mfma_f32_16x16x32_bf16 v[72:75], v[136:139], v[168:171], v[72:75]
	v_mfma_f32_16x16x32_bf16 v[72:75], v[140:143], v[172:175], v[72:75]
	v_mfma_f32_16x16x32_bf16 v[76:79], v[132:135], v[172:175], v[76:79]
	v_mfma_f32_16x16x32_bf16 v[76:79], v[128:131], v[168:171], v[76:79]
	s_setprio 0
	s_barrier
	s_add_i32 s69, s66, s51
	v_lshl_add_u64 v[216:217], s[42:43], 0, v[178:179]
	s_mov_b32 m0, s69
	ds_read_b128 v[192:195], v210
	ds_read_b128 v[196:199], v210 offset:1024
	ds_read_b128 v[200:203], v210 offset:2048
	ds_read_b128 v[212:215], v210 offset:3072
	global_load_lds_dwordx4 v[216:217], off
	v_lshl_add_u64 v[218:219], s[42:43], 0, v[182:183]
	s_add_i32 m0, s69, 0x2000
	s_nop 0
	global_load_lds_dwordx4 v[218:219], off
	s_barrier
	s_waitcnt lgkmcnt(0)
	s_setprio 1
	s_waitcnt lgkmcnt(0)
	v_mfma_f32_16x16x32_bf16 v[116:119], v[192:195], v[144:147], v[116:119]
	v_mfma_f32_16x16x32_bf16 v[116:119], v[196:199], v[148:151], v[116:119]
	v_mfma_f32_16x16x32_bf16 v[112:115], v[212:215], v[148:151], v[112:115]
	v_mfma_f32_16x16x32_bf16 v[112:115], v[200:203], v[144:147], v[112:115]
	v_mfma_f32_16x16x32_bf16 v[96:99], v[200:203], v[152:155], v[96:99]
	v_mfma_f32_16x16x32_bf16 v[96:99], v[212:215], v[156:159], v[96:99]
	v_mfma_f32_16x16x32_bf16 v[100:103], v[196:199], v[156:159], v[100:103]
	v_mfma_f32_16x16x32_bf16 v[100:103], v[192:195], v[152:155], v[100:103]
	v_mfma_f32_16x16x32_bf16 v[84:87], v[192:195], v[160:163], v[84:87]
	v_mfma_f32_16x16x32_bf16 v[84:87], v[196:199], v[164:167], v[84:87]
	v_mfma_f32_16x16x32_bf16 v[80:83], v[212:215], v[164:167], v[80:83]
	v_mfma_f32_16x16x32_bf16 v[80:83], v[200:203], v[160:163], v[80:83]
	v_mfma_f32_16x16x32_bf16 v[64:67], v[200:203], v[168:171], v[64:67]
	v_mfma_f32_16x16x32_bf16 v[64:67], v[212:215], v[172:175], v[64:67]
	v_mfma_f32_16x16x32_bf16 v[68:71], v[196:199], v[172:175], v[68:71]
	v_mfma_f32_16x16x32_bf16 v[68:71], v[192:195], v[168:171], v[68:71]
	s_setprio 0
	s_mov_b32 m0, s54
	v_lshl_add_u64 v[220:221], s[44:45], 0, v[176:177]
	s_barrier
	ds_read_b128 v[144:147], v209 offset:16384
	ds_read_b128 v[148:151], v209 offset:17408
	ds_read_b128 v[152:155], v209 offset:18432
	ds_read_b128 v[156:159], v209 offset:19456
	ds_read_b128 v[160:163], v209 offset:20480
	ds_read_b128 v[164:167], v209 offset:21504
	ds_read_b128 v[168:171], v209 offset:22528
	ds_read_b128 v[172:175], v209 offset:23552
	global_load_lds_dwordx4 v[220:221], off
	v_lshl_add_u64 v[222:223], s[44:45], 0, v[180:181]
	s_mov_b32 m0, s55
	s_nop 0
	global_load_lds_dwordx4 v[222:223], off
	s_barrier
	s_waitcnt lgkmcnt(0)
	s_setprio 1
	s_waitcnt lgkmcnt(0)
	v_mfma_f32_16x16x32_bf16 v[60:63], v[128:131], v[144:147], v[60:63]
	v_mfma_f32_16x16x32_bf16 v[60:63], v[132:135], v[148:151], v[60:63]
	v_mfma_f32_16x16x32_bf16 v[56:59], v[140:143], v[148:151], v[56:59]
	v_mfma_f32_16x16x32_bf16 v[56:59], v[136:139], v[144:147], v[56:59]
	v_mfma_f32_16x16x32_bf16 v[40:43], v[136:139], v[152:155], v[40:43]
	v_mfma_f32_16x16x32_bf16 v[40:43], v[140:143], v[156:159], v[40:43]
	v_mfma_f32_16x16x32_bf16 v[44:47], v[132:135], v[156:159], v[44:47]
	v_mfma_f32_16x16x32_bf16 v[44:47], v[128:131], v[152:155], v[44:47]
	v_mfma_f32_16x16x32_bf16 v[28:31], v[128:131], v[160:163], v[28:31]
	v_mfma_f32_16x16x32_bf16 v[28:31], v[132:135], v[164:167], v[28:31]
	v_mfma_f32_16x16x32_bf16 v[24:27], v[140:143], v[164:167], v[24:27]
	v_mfma_f32_16x16x32_bf16 v[24:27], v[136:139], v[160:163], v[24:27]
	v_mfma_f32_16x16x32_bf16 v[8:11], v[136:139], v[168:171], v[8:11]
	v_mfma_f32_16x16x32_bf16 v[8:11], v[140:143], v[172:175], v[8:11]
	v_mfma_f32_16x16x32_bf16 v[12:15], v[132:135], v[172:175], v[12:15]
	v_mfma_f32_16x16x32_bf16 v[12:15], v[128:131], v[168:171], v[12:15]
	s_setprio 0
	s_barrier
; #define PG8_STAGE(bufoff, gbase, voff) do { _Pragma("unroll") for (int _i = 0; _i < 2; ++_i) \
;         __builtin_amdgcn_global_load_lds((const unsigned*)((const char*)(gbase) + (voff)[_i]), (LAS unsigned*)(lds + (bufoff) + ldsw + _i * 8192), 16, 0, 0); } while (0)
; #define PG8_LDA(dst, b, h) do { _Pragma("unroll") for (int m = 0; m < 4; ++m) _Pragma("unroll") for (int k = 0; k < 2; ++k) dst[m][k] = *(const LAS bf16x8*)(lds + PG8_SA(b, h) + aoff + m * 2048 + k * 1024); } while (0)
; #define PG8_LDB(dst, b, h) do { _Pragma("unroll") for (int n = 0; n < 2; ++n) _Pragma("unroll") for (int k = 0; k < 2; ++k) dst[n][k] = *(const LAS bf16x8*)(lds + PG8_SB(b, h) + boff + n * 2048 + k * 1024); } while (0)
; #define PG8_MMA(ai, bj, At, Bt) do { __builtin_amdgcn_s_setprio(1); _Pragma("unroll") for (int m = 0; m < 4; ++m) _Pragma("unroll") for (int n = 0; n < 2; ++n) _Pragma("unroll") for (int k = 0; k < 2; ++k) \
;         acc[ai][bj][m][n] = __builtin_amdgcn_mfma_f32_16x16x32_bf16(Bt[n][k], At[m][k], acc[ai][bj][m][n], 0, 0, 0); __builtin_amdgcn_s_setprio(0); } while (0)
; #define PG8_WAIT_V(n) asm volatile("s_waitcnt vmcnt(" #n ")" ::: "memory")
; #define PG8_WAIT_L(n) asm volatile("s_waitcnt lgkmcnt(" #n ")" ::: "memory")
; #define PG8_BAR __builtin_amdgcn_s_barrier()
; #define PG8_SCHED __builtin_amdgcn_sched_barrier(0)
; template <class Epi, class Ptrs>
; __device__ __forceinline__ void gemm_phase(LAS unsigned char* lds, const int K, const StaticOrder& S, const Ptrs& P, const Epi& E) {
;     ...
;             PG8_STAGE(PG8_SB(0, 1), b2 + hstep, voffB);
;             PG8_WAIT_V(6); PG8_BAR; PG8_MMA(1, 1, At, B1); PG8_BAR;
;             PG8_LDB(B0, 1, 0); PG8_SCHED; PG8_LDA(At, 1, 0); PG8_STAGE(PG8_SA(0, 1), a2 + hstep, voffA);
;             PG8_WAIT_L(8); PG8_BAR; PG8_WAIT_L(0); PG8_MMA(0, 0, At, B0); PG8_BAR; PG8_SCHED;
;             PG8_LDB(B1, 1, 1); PG8_STAGE(PG8_SB(1, 0), b3, voffB);
;             PG8_BAR; PG8_WAIT_L(0); PG8_MMA(0, 1, At, B1); PG8_BAR;
;             PG8_LDA(At, 1, 1); PG8_STAGE(PG8_SA(1, 0), a3, voffA);
	s_add_u32 s70, s42, 0x40000
	s_addc_u32 s71, s43, 0
	s_add_i32 s69, s67, s51
	v_lshl_add_u64 v[128:129], s[70:71], 0, v[178:179]
	s_mov_b32 m0, s69
	s_nop 0
	global_load_lds_dwordx4 v[128:129], off
	v_lshl_add_u64 v[128:129], s[70:71], 0, v[182:183]
	s_add_i32 m0, s69, 0x2000
	s_nop 0
	global_load_lds_dwordx4 v[128:129], off
	s_waitcnt vmcnt(6)
	s_barrier
	s_setprio 1
	v_mfma_f32_16x16x32_bf16 v[52:55], v[192:195], v[144:147], v[52:55]
	v_mfma_f32_16x16x32_bf16 v[52:55], v[196:199], v[148:151], v[52:55]
	v_mfma_f32_16x16x32_bf16 v[48:51], v[212:215], v[148:151], v[48:51]
	v_mfma_f32_16x16x32_bf16 v[48:51], v[200:203], v[144:147], v[48:51]
	v_mfma_f32_16x16x32_bf16 v[32:35], v[200:203], v[152:155], v[32:35]
	v_mfma_f32_16x16x32_bf16 v[32:35], v[212:215], v[156:159], v[32:35]
	v_mfma_f32_16x16x32_bf16 v[36:39], v[196:199], v[156:159], v[36:39]
	v_mfma_f32_16x16x32_bf16 v[36:39], v[192:195], v[152:155], v[36:39]
	v_mfma_f32_16x16x32_bf16 v[20:23], v[192:195], v[160:163], v[20:23]
	v_mfma_f32_16x16x32_bf16 v[20:23], v[196:199], v[164:167], v[20:23]
	v_mfma_f32_16x16x32_bf16 v[16:19], v[212:215], v[164:167], v[16:19]
	v_mfma_f32_16x16x32_bf16 v[16:19], v[200:203], v[160:163], v[16:19]
	v_mfma_f32_16x16x32_bf16 v[0:3], v[200:203], v[168:171], v[0:3]
	v_mfma_f32_16x16x32_bf16 v[0:3], v[212:215], v[172:175], v[0:3]
	v_mfma_f32_16x16x32_bf16 v[4:7], v[196:199], v[172:175], v[4:7]
	v_mfma_f32_16x16x32_bf16 v[4:7], v[192:195], v[168:171], v[4:7]
	s_setprio 0
	s_add_i32 s69, 0, 0x18000
	v_add_u32_e32 v140, s69, v205
	s_barrier
	ds_read_b128 v[128:131], v140
	ds_read_b128 v[132:135], v140 offset:1024
	ds_read_b128 v[136:139], v140 offset:2048
	ds_read_b128 v[140:143], v140 offset:3072
	s_add_u32 s44, s44, 0x40000
	s_addc_u32 s45, s45, 0
	s_mov_b32 m0, s56
	v_lshl_add_u64 v[192:193], s[44:45], 0, v[176:177]
	ds_read_b128 v[144:147], v209 offset:32768
	ds_read_b128 v[148:151], v209 offset:33792
	ds_read_b128 v[152:155], v209 offset:34816
	ds_read_b128 v[156:159], v209 offset:35840
	ds_read_b128 v[160:163], v209 offset:36864
	ds_read_b128 v[164:167], v209 offset:37888
	ds_read_b128 v[168:171], v209 offset:38912
	ds_read_b128 v[172:175], v209 offset:39936
	global_load_lds_dwordx4 v[192:193], off
	v_lshl_add_u64 v[192:193], s[44:45], 0, v[180:181]
	s_mov_b32 m0, s57
	s_nop 0
	global_load_lds_dwordx4 v[192:193], off
	s_waitcnt lgkmcnt(8)
	s_barrier
	s_waitcnt lgkmcnt(0)
	s_setprio 1
	s_waitcnt lgkmcnt(0)
	v_mfma_f32_16x16x32_bf16 v[124:127], v[128:131], v[144:147], v[124:127]
	v_mfma_f32_16x16x32_bf16 v[124:127], v[132:135], v[148:151], v[124:127]
	v_mfma_f32_16x16x32_bf16 v[120:123], v[140:143], v[148:151], v[120:123]
	v_mfma_f32_16x16x32_bf16 v[120:123], v[136:139], v[144:147], v[120:123]
	v_mfma_f32_16x16x32_bf16 v[104:107], v[136:139], v[152:155], v[104:107]
	v_mfma_f32_16x16x32_bf16 v[104:107], v[140:143], v[156:159], v[104:107]
	v_mfma_f32_16x16x32_bf16 v[108:111], v[132:135], v[156:159], v[108:111]
	v_mfma_f32_16x16x32_bf16 v[108:111], v[128:131], v[152:155], v[108:111]
	v_mfma_f32_16x16x32_bf16 v[92:95], v[128:131], v[160:163], v[92:95]
	v_mfma_f32_16x16x32_bf16 v[92:95], v[132:135], v[164:167], v[92:95]
	v_mfma_f32_16x16x32_bf16 v[88:91], v[140:143], v[164:167], v[88:91]
	v_mfma_f32_16x16x32_bf16 v[88:91], v[136:139], v[160:163], v[88:91]
	v_mfma_f32_16x16x32_bf16 v[72:75], v[136:139], v[168:171], v[72:75]
	v_mfma_f32_16x16x32_bf16 v[72:75], v[140:143], v[172:175], v[72:75]
	v_mfma_f32_16x16x32_bf16 v[76:79], v[132:135], v[172:175], v[76:79]
	v_mfma_f32_16x16x32_bf16 v[76:79], v[128:131], v[168:171], v[76:79]
	s_setprio 0
	s_barrier
	s_add_i32 s44, 0, 0x1c000
	s_add_i32 s45, s69, s51
	v_add_u32_e32 v211, s44, v205
	v_lshl_add_u64 v[216:217], v[216:217], 0, s[18:19]
	s_mov_b32 m0, s45
	ds_read_b128 v[192:195], v211
	ds_read_b128 v[196:199], v211 offset:1024
	ds_read_b128 v[200:203], v211 offset:2048
	ds_read_b128 v[212:215], v211 offset:3072
	global_load_lds_dwordx4 v[216:217], off
	v_lshl_add_u64 v[216:217], v[218:219], 0, s[18:19]
	s_add_i32 m0, s45, 0x2000
	s_nop 0
	global_load_lds_dwordx4 v[216:217], off
	s_barrier
	s_waitcnt lgkmcnt(0)
	s_setprio 1
	s_waitcnt lgkmcnt(0)
	v_mfma_f32_16x16x32_bf16 v[116:119], v[192:195], v[144:147], v[116:119]
	v_mfma_f32_16x16x32_bf16 v[116:119], v[196:199], v[148:151], v[116:119]
	v_mfma_f32_16x16x32_bf16 v[112:115], v[212:215], v[148:151], v[112:115]
	v_mfma_f32_16x16x32_bf16 v[112:115], v[200:203], v[144:147], v[112:115]
	v_mfma_f32_16x16x32_bf16 v[96:99], v[200:203], v[152:155], v[96:99]
	v_mfma_f32_16x16x32_bf16 v[96:99], v[212:215], v[156:159], v[96:99]
	v_mfma_f32_16x16x32_bf16 v[100:103], v[196:199], v[156:159], v[100:103]
	v_mfma_f32_16x16x32_bf16 v[100:103], v[192:195], v[152:155], v[100:103]
	v_mfma_f32_16x16x32_bf16 v[84:87], v[192:195], v[160:163], v[84:87]
	v_mfma_f32_16x16x32_bf16 v[84:87], v[196:199], v[164:167], v[84:87]
	v_mfma_f32_16x16x32_bf16 v[80:83], v[212:215], v[164:167], v[80:83]
	v_mfma_f32_16x16x32_bf16 v[80:83], v[200:203], v[160:163], v[80:83]
	v_mfma_f32_16x16x32_bf16 v[64:67], v[200:203], v[168:171], v[64:67]
	v_mfma_f32_16x16x32_bf16 v[64:67], v[212:215], v[172:175], v[64:67]
	v_mfma_f32_16x16x32_bf16 v[68:71], v[196:199], v[172:175], v[68:71]
	v_mfma_f32_16x16x32_bf16 v[68:71], v[192:195], v[168:171], v[68:71]
	s_setprio 0
	s_mov_b32 m0, s63
	v_lshl_add_u64 v[216:217], v[220:221], 0, s[18:19]
	s_barrier
	ds_read_b128 v[144:147], v209 offset:49152
	ds_read_b128 v[148:151], v209 offset:50176
	ds_read_b128 v[152:155], v209 offset:51200
	ds_read_b128 v[156:159], v209 offset:52224
	ds_read_b128 v[160:163], v209 offset:53248
	ds_read_b128 v[164:167], v209 offset:54272
	ds_read_b128 v[168:171], v209 offset:55296
	ds_read_b128 v[172:175], v209 offset:56320
	global_load_lds_dwordx4 v[216:217], off
	v_lshl_add_u64 v[216:217], v[222:223], 0, s[18:19]
	s_mov_b32 m0, s64
	s_nop 0
	global_load_lds_dwordx4 v[216:217], off
	s_barrier
; __device__ __forceinline__ unsigned cvt_pk_bf16(float lo, float hi) { unsigned r; asm volatile("v_cvt_pk_bf16_f32 %0, %1, %2" : "=v"(r) : "v"(lo), "v"(hi)); return r; }
; __device__ __forceinline__ float x16_sum(float x) { auto s = __builtin_amdgcn_permlane16_swap(__float_as_uint(x), __float_as_uint(x), false, false); return __uint_as_float(s[0]) + __uint_as_float(s[1]); }
; #define PG8_WAIT_V(n) asm volatile("s_waitcnt vmcnt(" #n ")" ::: "memory")
; template <class Epi, class Ptrs>
; __device__ __forceinline__ void gemm_phase(LAS unsigned char* lds, const int K, const StaticOrder& S, const Ptrs& P, const Epi& E) {
;     ...
;             PG8_BAR; PG8_WAIT_L(0); PG8_MMA(1, 0, At, B0); PG8_BAR; PG8_SCHED;
;             PG8_STAGE(PG8_SB(1, 1), b3 + hstep, voffB);
;             PG8_WAIT_V(6); PG8_BAR; PG8_MMA(1, 1, At, B1); PG8_BAR;
;     __device__ __forceinline__ void operator()(const f32x4 (&acc)[2][2][4][2], const Unit& u, int ui, int wr, int wc, int fr, int fq) const {
;         const int row0 = u.pm * 256 + wr * 64 + fr, col0 = u.pn * 256 + wc * 32 + 8 * fq;
;         const float* xb0 = (u.pm * 256 < MP) ? xp : xs - (size_t)MP * DM;
; #pragma unroll
;         for (int ai = 0; ai < 2; ++ai) {
;             f32x4 xv[4][2][2];
; #pragma unroll
;             for (int m = 0; m < 4; ++m)
; #pragma unroll
;                 for (int bj = 0; bj < 2; ++bj) { const float* p = xb0 + (size_t)(row0 + ai * 128 + m * 16) * DM + col0 + bj * 128; xv[m][bj][0] = *(const f32x4*)p; xv[m][bj][1] = *(const f32x4*)(p + 4); }
; #pragma unroll
;             for (int m = 0; m < 4; ++m) { const int row = row0 + ai * 128 + m * 16; const size_t off = (size_t)row * DM + col0; float ss = 0.f;
; #pragma unroll
;                 for (int bj = 0; bj < 2; ++bj) {
;                     const f32x4 v0 = acc[ai][bj][m][0] + xv[m][bj][0], v1 = acc[ai][bj][m][1] + xv[m][bj][1];
;                     u32x4 w; w.x = cvt_pk_bf16(v0[0], v0[1]); w.y = cvt_pk_bf16(v0[2], v0[3]); w.z = cvt_pk_bf16(v1[0], v1[1]); w.w = cvt_pk_bf16(v1[2], v1[3]);
;                     *(u32x4*)(xb + off + bj * 128) = w;
;                     ss += (v0[0] * v0[0] + v0[1] * v0[1]) + (v0[2] * v0[2] + v0[3] * v0[3]) + (v1[0] * v1[0] + v1[1] * v1[1]) + (v1[2] * v1[2] + v1[3] * v1[3]); }
;                 ss = x32_sum(x16_sum(ss));
;                 if (fq == 0) part[(size_t)row * 16 + u.pn * 4 + wc] = ss; }
	s_waitcnt lgkmcnt(0)
	s_setprio 1
	s_waitcnt lgkmcnt(0)
	v_mfma_f32_16x16x32_bf16 v[60:63], v[128:131], v[144:147], v[60:63]
	v_mfma_f32_16x16x32_bf16 v[60:63], v[132:135], v[148:151], v[60:63]
	v_mfma_f32_16x16x32_bf16 v[56:59], v[140:143], v[148:151], v[56:59]
	v_mfma_f32_16x16x32_bf16 v[56:59], v[136:139], v[144:147], v[56:59]
	v_mfma_f32_16x16x32_bf16 v[40:43], v[136:139], v[152:155], v[40:43]
	v_mfma_f32_16x16x32_bf16 v[40:43], v[140:143], v[156:159], v[40:43]
	v_mfma_f32_16x16x32_bf16 v[44:47], v[132:135], v[156:159], v[44:47]
	v_mfma_f32_16x16x32_bf16 v[44:47], v[128:131], v[152:155], v[44:47]
	v_mfma_f32_16x16x32_bf16 v[28:31], v[128:131], v[160:163], v[28:31]
	v_mfma_f32_16x16x32_bf16 v[28:31], v[132:135], v[164:167], v[28:31]
	v_mfma_f32_16x16x32_bf16 v[24:27], v[140:143], v[164:167], v[24:27]
	v_mfma_f32_16x16x32_bf16 v[24:27], v[136:139], v[160:163], v[24:27]
	v_mfma_f32_16x16x32_bf16 v[8:11], v[136:139], v[168:171], v[8:11]
	v_mfma_f32_16x16x32_bf16 v[8:11], v[140:143], v[172:175], v[8:11]
	v_mfma_f32_16x16x32_bf16 v[12:15], v[132:135], v[172:175], v[12:15]
	v_mfma_f32_16x16x32_bf16 v[12:15], v[128:131], v[168:171], v[12:15]
	s_setprio 0
	s_barrier
	s_add_u32 s42, s42, 0x40080
	s_addc_u32 s43, s43, 0
	s_add_i32 s44, s44, s51
	v_lshl_add_u64 v[128:129], s[42:43], 0, v[178:179]
	s_mov_b32 m0, s44
	s_nop 0
	global_load_lds_dwordx4 v[128:129], off
	v_lshl_add_u64 v[128:129], s[42:43], 0, v[182:183]
	s_add_i32 m0, s44, 0x2000
	s_nop 0
	global_load_lds_dwordx4 v[128:129], off
	s_waitcnt vmcnt(6)
	s_barrier
	s_setprio 1
	v_mfma_f32_16x16x32_bf16 v[52:55], v[192:195], v[144:147], v[52:55]
	v_mfma_f32_16x16x32_bf16 v[52:55], v[196:199], v[148:151], v[52:55]
	v_mfma_f32_16x16x32_bf16 v[48:51], v[212:215], v[148:151], v[48:51]
	v_mfma_f32_16x16x32_bf16 v[48:51], v[200:203], v[144:147], v[48:51]
	v_mfma_f32_16x16x32_bf16 v[32:35], v[200:203], v[152:155], v[32:35]
	v_mfma_f32_16x16x32_bf16 v[32:35], v[212:215], v[156:159], v[32:35]
	v_mfma_f32_16x16x32_bf16 v[36:39], v[196:199], v[156:159], v[36:39]
	v_mfma_f32_16x16x32_bf16 v[36:39], v[192:195], v[152:155], v[36:39]
	v_mfma_f32_16x16x32_bf16 v[20:23], v[192:195], v[160:163], v[20:23]
	v_mfma_f32_16x16x32_bf16 v[20:23], v[196:199], v[164:167], v[20:23]
	v_mfma_f32_16x16x32_bf16 v[16:19], v[212:215], v[164:167], v[16:19]
	v_mfma_f32_16x16x32_bf16 v[16:19], v[200:203], v[160:163], v[16:19]
	v_mfma_f32_16x16x32_bf16 v[0:3], v[200:203], v[168:171], v[0:3]
	v_mfma_f32_16x16x32_bf16 v[0:3], v[212:215], v[172:175], v[0:3]
	v_mfma_f32_16x16x32_bf16 v[4:7], v[196:199], v[172:175], v[4:7]
	v_mfma_f32_16x16x32_bf16 v[4:7], v[192:195], v[168:171], v[4:7]
	s_setprio 0
	s_add_i32 s41, s41, 2
	s_add_u32 s38, s38, 0x100
	s_addc_u32 s39, s39, 0
	s_add_u32 s21, s21, 0x100
	s_addc_u32 s23, s23, 0
	s_cmp_gt_u32 s41, 13
	s_barrier
	s_cbranch_scc0 .LBB0_353
	s_cmpk_lt_i32 s40, 0x80
	v_lshl_add_u32 v194, s40, 8, v204
	v_lshl_or_b32 v192, s12, 8, v206
	s_cselect_b32 s21, s37, s61
	s_cselect_b32 s23, s36, s60
	v_mov_b32_e32 v128, s23
	v_mov_b32_e32 v129, s21
	v_ashrrev_i32_e32 v193, 31, v192
	v_ashrrev_i32_e32 v195, 31, v194
	v_lshl_add_u64 v[196:197], v[192:193], 2, v[128:129]
	v_lshlrev_b64 v[128:129], 12, v[194:195]
	v_or_b32_e32 v202, 16, v194
	v_or_b32_e32 v200, 32, v194
	v_or_b32_e32 v198, 48, v194
	v_lshl_add_u64 v[128:129], v[196:197], 0, v[128:129]
	v_ashrrev_i32_e32 v203, 31, v202
	v_ashrrev_i32_e32 v201, 31, v200
	v_ashrrev_i32_e32 v199, 31, v198
	global_load_dwordx4 v[212:215], v[128:129], off
	global_load_dwordx4 v[216:219], v[128:129], off offset:16
	global_load_dwordx4 v[220:223], v[128:129], off offset:512
	global_load_dwordx4 v[224:227], v[128:129], off offset:528
	v_lshlrev_b64 v[128:129], 12, v[202:203]
	v_lshlrev_b64 v[130:131], 12, v[200:201]
	v_lshlrev_b64 v[132:133], 12, v[198:199]
	v_lshl_add_u64 v[128:129], v[196:197], 0, v[128:129]
	v_lshl_add_u64 v[130:131], v[196:197], 0, v[130:131]
	v_lshl_add_u64 v[132:133], v[196:197], 0, v[132:133]
	global_load_dwordx4 v[168:171], v[128:129], off offset:16
	global_load_dwordx4 v[172:175], v[128:129], off
	global_load_dwordx4 v[160:163], v[128:129], off offset:528
	global_load_dwordx4 v[164:167], v[128:129], off offset:512
	global_load_dwordx4 v[152:155], v[130:131], off offset:16
	global_load_dwordx4 v[156:159], v[130:131], off
	global_load_dwordx4 v[144:147], v[130:131], off offset:528
	global_load_dwordx4 v[148:151], v[130:131], off offset:512
	global_load_dwordx4 v[136:139], v[132:133], off offset:16
	global_load_dwordx4 v[140:143], v[132:133], off
	s_nop 0
	global_load_dwordx4 v[128:131], v[132:133], off offset:528
	s_nop 0
	global_load_dwordx4 v[132:135], v[132:133], off offset:512
	v_lshlrev_b64 v[228:229], 11, v[194:195]
	v_lshl_add_u64 v[228:229], s[14:15], 0, v[228:229]
	v_lshl_add_u64 v[228:229], v[192:193], 1, v[228:229]
	s_lshl_b32 s38, s12, 2
	s_ashr_i32 s39, s38, 31
	s_waitcnt vmcnt(0)
	v_pk_add_f32 v[126:127], v[126:127], v[214:215]
	v_pk_add_f32 v[124:125], v[124:125], v[212:213]
	v_pk_add_f32 v[118:119], v[118:119], v[222:223]
	v_pk_add_f32 v[116:117], v[116:117], v[220:221]
	v_pk_add_f32 v[120:121], v[120:121], v[216:217]
	v_pk_add_f32 v[214:215], v[112:113], v[224:225]
	v_cvt_pk_bf16_f32 v112, v124, v125
	v_cvt_pk_bf16_f32 v113, v126, v127
	v_mul_f32_e32 v125, v125, v125
	v_mul_f32_e32 v127, v127, v127
	v_mul_f32_e32 v211, v117, v117
	v_mul_f32_e32 v216, v119, v119
	v_pk_add_f32 v[122:123], v[122:123], v[218:219]
	v_pk_add_f32 v[212:213], v[114:115], v[226:227]
	v_cvt_pk_bf16_f32 v114, v120, v121
	v_cvt_pk_bf16_f32 v115, v122, v123
	v_mul_f32_e32 v121, v121, v121
	v_mul_f32_e32 v217, v215, v215
	global_store_dwordx4 v[228:229], v[112:115], off
	v_fmac_f32_e32 v125, v124, v124
	v_fmac_f32_e32 v127, v126, v126
	v_cvt_pk_bf16_f32 v112, v116, v117
	v_fmac_f32_e32 v211, v116, v116
	v_fmac_f32_e32 v216, v118, v118
	v_mul_f32_e32 v123, v123, v123
	v_mul_f32_e32 v218, v213, v213
	v_fmac_f32_e32 v121, v120, v120
	v_cvt_pk_bf16_f32 v113, v118, v119
	v_cvt_pk_bf16_f32 v114, v214, v215
	v_cvt_pk_bf16_f32 v115, v212, v213
	v_fmac_f32_e32 v217, v214, v214
	v_add_f32_e32 v116, v125, v127
	global_store_dwordx4 v[228:229], v[112:115], off offset:256
	v_fmac_f32_e32 v123, v122, v122
	v_fmac_f32_e32 v218, v212, v212
	v_add_f32_e32 v112, v211, v216
	v_add_f32_e32 v113, v116, v121
	v_add_f32_e32 v112, v112, v217
	v_add_f32_e32 v113, v123, v113
	v_add_f32_e32 v112, v218, v112
	v_add_f32_e32 v112, v113, v112
	v_mov_b32_e32 v113, v112
	s_nop 1
	v_permlane16_swap_b32_e32 v112, v113
	v_add_f32_e32 v112, v112, v113
	v_mov_b32_e32 v113, v112
	s_nop 1
	v_permlane32_swap_b32_e32 v112, v113
	s_and_saveexec_b64 s[40:41], s[6:7]
	s_cbranch_execz .LBB0_356
	v_lshlrev_b64 v[114:115], 6, v[194:195]
	v_lshl_add_u64 v[114:115], s[16:17], 0, v[114:115]
	v_lshl_add_u64 v[114:115], s[38:39], 2, v[114:115]
	s_lshl_b32 s12, s62, 2
	v_lshl_add_u64 v[114:115], v[114:115], 0, s[12:13]
	v_add_f32_e32 v112, v112, v113
	global_store_dword v[114:115], v112, off

; #define PG8_STAGE(bufoff, gbase, voff) do { _Pragma("unroll") for (int _i = 0; _i < 2; ++_i) \
;         __builtin_amdgcn_global_load_lds((const unsigned*)((const char*)(gbase) + (voff)[_i]), (LAS unsigned*)(lds + (bufoff) + ldsw + _i * 8192), 16, 0, 0); } while (0)
; #define PG8_LDA(dst, b, h) do { _Pragma("unroll") for (int m = 0; m < 4; ++m) _Pragma("unroll") for (int k = 0; k < 2; ++k) dst[m][k] = *(const LAS bf16x8*)(lds + PG8_SA(b, h) + aoff + m * 2048 + k * 1024); } while (0)
; #define PG8_LDB(dst, b, h) do { _Pragma("unroll") for (int n = 0; n < 2; ++n) _Pragma("unroll") for (int k = 0; k < 2; ++k) dst[n][k] = *(const LAS bf16x8*)(lds + PG8_SB(b, h) + boff + n * 2048 + k * 1024); } while (0)
; #define PG8_MMA(ai, bj, At, Bt) do { __builtin_amdgcn_s_setprio(1); _Pragma("unroll") for (int m = 0; m < 4; ++m) _Pragma("unroll") for (int n = 0; n < 2; ++n) _Pragma("unroll") for (int k = 0; k < 2; ++k) \
;         acc[ai][bj][m][n] = __builtin_amdgcn_mfma_f32_16x16x32_bf16(Bt[n][k], At[m][k], acc[ai][bj][m][n], 0, 0, 0); __builtin_amdgcn_s_setprio(0); } while (0)
; #define PG8_WAIT_L(n) asm volatile("s_waitcnt lgkmcnt(" #n ")" ::: "memory")
; #define PG8_BAR __builtin_amdgcn_s_barrier()
; #define PG8_SCHED __builtin_amdgcn_sched_barrier(0)
; template <class Epi, class Ptrs>
; __device__ __forceinline__ void gemm_phase(LAS unsigned char* lds, const int K, const StaticOrder& S, const Ptrs& P, const Epi& E) {
;     ...
;             PG8_LDB(B0, 0, 0); PG8_SCHED; PG8_LDA(At, 0, 0); PG8_STAGE(PG8_SA(1, 1), a1 + hstep, voffA);
;             PG8_WAIT_L(8); PG8_BAR; PG8_WAIT_L(0); PG8_MMA(0, 0, At, B0); PG8_BAR; PG8_SCHED;
;             PG8_LDB(B1, 0, 1); PG8_STAGE(PG8_SB(0, 0), b2, voffB);
;             PG8_BAR; PG8_WAIT_L(0); PG8_MMA(0, 1, At, B1); PG8_BAR;
;             PG8_LDA(At, 0, 1); PG8_STAGE(PG8_SA(0, 0), a2, voffA);
;             PG8_BAR; PG8_WAIT_L(0); PG8_MMA(1, 0, At, B0); PG8_BAR; PG8_SCHED;
.LBB0_433:
	ds_read_b128 v[152:155], v149
	ds_read_b128 v[156:159], v149 offset:1024
	ds_read_b128 v[160:163], v149 offset:2048
	ds_read_b128 v[164:167], v149 offset:3072
	s_add_u32 s42, s40, 0xfffc0080
	s_addc_u32 s43, s41, -1
	s_cmp_eq_u32 s70, 12
	s_cselect_b32 s45, s1, s43
	s_cselect_b32 s44, s0, s42
	s_cselect_b32 s43, s37, s25
	s_cselect_b32 s42, s36, s23
	v_lshl_add_u64 v[144:145], s[40:41], 0, v[136:137]
	s_add_i32 m0, s39, 0xc000
	ds_read_b128 v[168:171], v150
	ds_read_b128 v[172:175], v150 offset:1024
	ds_read_b128 v[176:179], v150 offset:2048
	ds_read_b128 v[180:183], v150 offset:3072
	ds_read_b128 v[184:187], v150 offset:4096
	ds_read_b128 v[188:191], v150 offset:5120
	ds_read_b128 v[192:195], v150 offset:6144
	ds_read_b128 v[196:199], v150 offset:7168
	global_load_lds_dwordx4 v[144:145], off
	v_lshl_add_u64 v[144:145], s[40:41], 0, v[138:139]
	s_add_i32 m0, s39, 0xe000
	s_nop 0
	global_load_lds_dwordx4 v[144:145], off
	s_waitcnt lgkmcnt(8)
	s_barrier
	s_waitcnt lgkmcnt(0)
	s_setprio 1
	s_waitcnt lgkmcnt(0)
	v_mfma_f32_16x16x32_bf16 v[124:127], v[152:155], v[168:171], v[124:127]
	v_mfma_f32_16x16x32_bf16 v[124:127], v[156:159], v[172:175], v[124:127]
	v_mfma_f32_16x16x32_bf16 v[120:123], v[164:167], v[172:175], v[120:123]
	v_mfma_f32_16x16x32_bf16 v[120:123], v[160:163], v[168:171], v[120:123]
	v_mfma_f32_16x16x32_bf16 v[104:107], v[160:163], v[176:179], v[104:107]
	v_mfma_f32_16x16x32_bf16 v[104:107], v[164:167], v[180:183], v[104:107]
	v_mfma_f32_16x16x32_bf16 v[108:111], v[156:159], v[180:183], v[108:111]
	v_mfma_f32_16x16x32_bf16 v[108:111], v[152:155], v[176:179], v[108:111]
	v_mfma_f32_16x16x32_bf16 v[92:95], v[152:155], v[184:187], v[92:95]
	v_mfma_f32_16x16x32_bf16 v[92:95], v[156:159], v[188:191], v[92:95]
	v_mfma_f32_16x16x32_bf16 v[88:91], v[164:167], v[188:191], v[88:91]
	v_mfma_f32_16x16x32_bf16 v[88:91], v[160:163], v[184:187], v[88:91]
	v_mfma_f32_16x16x32_bf16 v[72:75], v[160:163], v[192:195], v[72:75]
	v_mfma_f32_16x16x32_bf16 v[72:75], v[164:167], v[196:199], v[72:75]
	v_mfma_f32_16x16x32_bf16 v[76:79], v[156:159], v[196:199], v[76:79]
	v_mfma_f32_16x16x32_bf16 v[76:79], v[152:155], v[192:195], v[76:79]
	s_setprio 0
	s_barrier
	s_add_i32 s71, s63, s51
	v_lshl_add_u64 v[144:145], s[42:43], 0, v[130:131]
	s_mov_b32 m0, s71
	ds_read_b128 v[200:203], v151
	ds_read_b128 v[204:207], v151 offset:1024
	ds_read_b128 v[210:213], v151 offset:2048
	ds_read_b128 v[214:217], v151 offset:3072
	global_load_lds_dwordx4 v[144:145], off
	v_lshl_add_u64 v[218:219], s[42:43], 0, v[134:135]
	s_add_i32 m0, s71, 0x2000
	s_nop 0
	global_load_lds_dwordx4 v[218:219], off
	s_barrier
	s_waitcnt lgkmcnt(0)
	s_setprio 1
	s_waitcnt lgkmcnt(0)
	v_mfma_f32_16x16x32_bf16 v[116:119], v[200:203], v[168:171], v[116:119]
	v_mfma_f32_16x16x32_bf16 v[116:119], v[204:207], v[172:175], v[116:119]
	v_mfma_f32_16x16x32_bf16 v[112:115], v[214:217], v[172:175], v[112:115]
	v_mfma_f32_16x16x32_bf16 v[112:115], v[210:213], v[168:171], v[112:115]
	v_mfma_f32_16x16x32_bf16 v[96:99], v[210:213], v[176:179], v[96:99]
	v_mfma_f32_16x16x32_bf16 v[96:99], v[214:217], v[180:183], v[96:99]
	v_mfma_f32_16x16x32_bf16 v[100:103], v[204:207], v[180:183], v[100:103]
	v_mfma_f32_16x16x32_bf16 v[100:103], v[200:203], v[176:179], v[100:103]
	v_mfma_f32_16x16x32_bf16 v[84:87], v[200:203], v[184:187], v[84:87]
	v_mfma_f32_16x16x32_bf16 v[84:87], v[204:207], v[188:191], v[84:87]
	v_mfma_f32_16x16x32_bf16 v[80:83], v[214:217], v[188:191], v[80:83]
	v_mfma_f32_16x16x32_bf16 v[80:83], v[210:213], v[184:187], v[80:83]
	v_mfma_f32_16x16x32_bf16 v[64:67], v[210:213], v[192:195], v[64:67]
	v_mfma_f32_16x16x32_bf16 v[64:67], v[214:217], v[196:199], v[64:67]
	v_mfma_f32_16x16x32_bf16 v[68:71], v[204:207], v[196:199], v[68:71]
	v_mfma_f32_16x16x32_bf16 v[68:71], v[200:203], v[192:195], v[68:71]
	s_setprio 0
	s_mov_b32 m0, s39
	v_lshl_add_u64 v[220:221], s[44:45], 0, v[128:129]
	s_barrier
	ds_read_b128 v[168:171], v150 offset:16384
	ds_read_b128 v[172:175], v150 offset:17408
	ds_read_b128 v[176:179], v150 offset:18432
	ds_read_b128 v[180:183], v150 offset:19456
	ds_read_b128 v[184:187], v150 offset:20480
	ds_read_b128 v[188:191], v150 offset:21504
	ds_read_b128 v[192:195], v150 offset:22528
	ds_read_b128 v[196:199], v150 offset:23552
	global_load_lds_dwordx4 v[220:221], off
	v_lshl_add_u64 v[222:223], s[44:45], 0, v[132:133]
	s_mov_b32 m0, s56
	s_nop 0
	global_load_lds_dwordx4 v[222:223], off
	s_barrier
	s_waitcnt lgkmcnt(0)
	s_setprio 1
	s_waitcnt lgkmcnt(0)
	v_mfma_f32_16x16x32_bf16 v[60:63], v[152:155], v[168:171], v[60:63]
	v_mfma_f32_16x16x32_bf16 v[60:63], v[156:159], v[172:175], v[60:63]
	v_mfma_f32_16x16x32_bf16 v[56:59], v[164:167], v[172:175], v[56:59]
	v_mfma_f32_16x16x32_bf16 v[56:59], v[160:163], v[168:171], v[56:59]
	v_mfma_f32_16x16x32_bf16 v[40:43], v[160:163], v[176:179], v[40:43]
	v_mfma_f32_16x16x32_bf16 v[40:43], v[164:167], v[180:183], v[40:43]
	v_mfma_f32_16x16x32_bf16 v[44:47], v[156:159], v[180:183], v[44:47]
	v_mfma_f32_16x16x32_bf16 v[44:47], v[152:155], v[176:179], v[44:47]
	v_mfma_f32_16x16x32_bf16 v[28:31], v[152:155], v[184:187], v[28:31]
	v_mfma_f32_16x16x32_bf16 v[28:31], v[156:159], v[188:191], v[28:31]
	v_mfma_f32_16x16x32_bf16 v[24:27], v[164:167], v[188:191], v[24:27]
	v_mfma_f32_16x16x32_bf16 v[24:27], v[160:163], v[184:187], v[24:27]
	v_mfma_f32_16x16x32_bf16 v[8:11], v[160:163], v[192:195], v[8:11]
	v_mfma_f32_16x16x32_bf16 v[8:11], v[164:167], v[196:199], v[8:11]
	v_mfma_f32_16x16x32_bf16 v[12:15], v[156:159], v[196:199], v[12:15]
	v_mfma_f32_16x16x32_bf16 v[12:15], v[152:155], v[192:195], v[12:15]
	s_setprio 0
	s_barrier
; #define PG8_STAGE(bufoff, gbase, voff) do { _Pragma("unroll") for (int _i = 0; _i < 2; ++_i) \
;         __builtin_amdgcn_global_load_lds((const unsigned*)((const char*)(gbase) + (voff)[_i]), (LAS unsigned*)(lds + (bufoff) + ldsw + _i * 8192), 16, 0, 0); } while (0)
; #define PG8_LDA(dst, b, h) do { _Pragma("unroll") for (int m = 0; m < 4; ++m) _Pragma("unroll") for (int k = 0; k < 2; ++k) dst[m][k] = *(const LAS bf16x8*)(lds + PG8_SA(b, h) + aoff + m * 2048 + k * 1024); } while (0)
; #define PG8_LDB(dst, b, h) do { _Pragma("unroll") for (int n = 0; n < 2; ++n) _Pragma("unroll") for (int k = 0; k < 2; ++k) dst[n][k] = *(const LAS bf16x8*)(lds + PG8_SB(b, h) + boff + n * 2048 + k * 1024); } while (0)
; #define PG8_MMA(ai, bj, At, Bt) do { __builtin_amdgcn_s_setprio(1); _Pragma("unroll") for (int m = 0; m < 4; ++m) _Pragma("unroll") for (int n = 0; n < 2; ++n) _Pragma("unroll") for (int k = 0; k < 2; ++k) \
;         acc[ai][bj][m][n] = __builtin_amdgcn_mfma_f32_16x16x32_bf16(Bt[n][k], At[m][k], acc[ai][bj][m][n], 0, 0, 0); __builtin_amdgcn_s_setprio(0); } while (0)
; #define PG8_WAIT_V(n) asm volatile("s_waitcnt vmcnt(" #n ")" ::: "memory")
; #define PG8_WAIT_L(n) asm volatile("s_waitcnt lgkmcnt(" #n ")" ::: "memory")
; #define PG8_BAR __builtin_amdgcn_s_barrier()
; #define PG8_SCHED __builtin_amdgcn_sched_barrier(0)
; template <class Epi, class Ptrs>
; __device__ __forceinline__ void gemm_phase(LAS unsigned char* lds, const int K, const StaticOrder& S, const Ptrs& P, const Epi& E) {
;     ...
;             PG8_STAGE(PG8_SB(0, 1), b2 + hstep, voffB);
;             PG8_WAIT_V(6); PG8_BAR; PG8_MMA(1, 1, At, B1); PG8_BAR;
;             PG8_LDB(B0, 1, 0); PG8_SCHED; PG8_LDA(At, 1, 0); PG8_STAGE(PG8_SA(0, 1), a2 + hstep, voffA);
;             PG8_WAIT_L(8); PG8_BAR; PG8_WAIT_L(0); PG8_MMA(0, 0, At, B0); PG8_BAR; PG8_SCHED;
;             PG8_LDB(B1, 1, 1); PG8_STAGE(PG8_SB(1, 0), b3, voffB);
;             PG8_BAR; PG8_WAIT_L(0); PG8_MMA(0, 1, At, B1); PG8_BAR;
;             PG8_LDA(At, 1, 1); PG8_STAGE(PG8_SA(1, 0), a3, voffA);
	s_add_u32 s72, s42, 0x40000
	s_addc_u32 s73, s43, 0
	s_add_i32 s71, s64, s51
	v_lshl_add_u64 v[152:153], s[72:73], 0, v[130:131]
	s_mov_b32 m0, s71
	s_nop 0
	global_load_lds_dwordx4 v[152:153], off
	v_lshl_add_u64 v[152:153], s[72:73], 0, v[134:135]
	s_add_i32 m0, s71, 0x2000
	s_nop 0
	global_load_lds_dwordx4 v[152:153], off
	s_waitcnt vmcnt(6)
	s_barrier
	s_setprio 1
	v_mfma_f32_16x16x32_bf16 v[52:55], v[200:203], v[168:171], v[52:55]
	v_mfma_f32_16x16x32_bf16 v[52:55], v[204:207], v[172:175], v[52:55]
	v_mfma_f32_16x16x32_bf16 v[48:51], v[214:217], v[172:175], v[48:51]
	v_mfma_f32_16x16x32_bf16 v[48:51], v[210:213], v[168:171], v[48:51]
	v_mfma_f32_16x16x32_bf16 v[32:35], v[210:213], v[176:179], v[32:35]
	v_mfma_f32_16x16x32_bf16 v[32:35], v[214:217], v[180:183], v[32:35]
	v_mfma_f32_16x16x32_bf16 v[36:39], v[204:207], v[180:183], v[36:39]
	v_mfma_f32_16x16x32_bf16 v[36:39], v[200:203], v[176:179], v[36:39]
	v_mfma_f32_16x16x32_bf16 v[20:23], v[200:203], v[184:187], v[20:23]
	v_mfma_f32_16x16x32_bf16 v[20:23], v[204:207], v[188:191], v[20:23]
	v_mfma_f32_16x16x32_bf16 v[16:19], v[214:217], v[188:191], v[16:19]
	v_mfma_f32_16x16x32_bf16 v[16:19], v[210:213], v[184:187], v[16:19]
	v_mfma_f32_16x16x32_bf16 v[0:3], v[210:213], v[192:195], v[0:3]
	v_mfma_f32_16x16x32_bf16 v[0:3], v[214:217], v[196:199], v[0:3]
	v_mfma_f32_16x16x32_bf16 v[4:7], v[204:207], v[196:199], v[4:7]
	v_mfma_f32_16x16x32_bf16 v[4:7], v[200:203], v[192:195], v[4:7]
	s_setprio 0
	s_add_i32 s71, 0, 0x18000
	v_add_u32_e32 v164, s71, v147
	s_barrier
	ds_read_b128 v[152:155], v164
	ds_read_b128 v[156:159], v164 offset:1024
	ds_read_b128 v[160:163], v164 offset:2048
	ds_read_b128 v[164:167], v164 offset:3072
	s_add_u32 s44, s44, 0x40000
	s_addc_u32 s45, s45, 0
	s_mov_b32 m0, s57
	v_lshl_add_u64 v[200:201], s[44:45], 0, v[128:129]
	ds_read_b128 v[168:171], v150 offset:32768
	ds_read_b128 v[172:175], v150 offset:33792
	ds_read_b128 v[176:179], v150 offset:34816
	ds_read_b128 v[180:183], v150 offset:35840
	ds_read_b128 v[184:187], v150 offset:36864
	ds_read_b128 v[188:191], v150 offset:37888
	ds_read_b128 v[192:195], v150 offset:38912
	ds_read_b128 v[196:199], v150 offset:39936
	global_load_lds_dwordx4 v[200:201], off
	v_lshl_add_u64 v[200:201], s[44:45], 0, v[132:133]
	s_mov_b32 m0, s58
	s_nop 0
	global_load_lds_dwordx4 v[200:201], off
	s_waitcnt lgkmcnt(8)
	s_barrier
	s_waitcnt lgkmcnt(0)
	s_setprio 1
	s_waitcnt lgkmcnt(0)
	v_mfma_f32_16x16x32_bf16 v[124:127], v[152:155], v[168:171], v[124:127]
	v_mfma_f32_16x16x32_bf16 v[124:127], v[156:159], v[172:175], v[124:127]
	v_mfma_f32_16x16x32_bf16 v[120:123], v[164:167], v[172:175], v[120:123]
	v_mfma_f32_16x16x32_bf16 v[120:123], v[160:163], v[168:171], v[120:123]
	v_mfma_f32_16x16x32_bf16 v[104:107], v[160:163], v[176:179], v[104:107]
	v_mfma_f32_16x16x32_bf16 v[104:107], v[164:167], v[180:183], v[104:107]
	v_mfma_f32_16x16x32_bf16 v[108:111], v[156:159], v[180:183], v[108:111]
	v_mfma_f32_16x16x32_bf16 v[108:111], v[152:155], v[176:179], v[108:111]
	v_mfma_f32_16x16x32_bf16 v[92:95], v[152:155], v[184:187], v[92:95]
	v_mfma_f32_16x16x32_bf16 v[92:95], v[156:159], v[188:191], v[92:95]
	v_mfma_f32_16x16x32_bf16 v[88:91], v[164:167], v[188:191], v[88:91]
	v_mfma_f32_16x16x32_bf16 v[88:91], v[160:163], v[184:187], v[88:91]
	v_mfma_f32_16x16x32_bf16 v[72:75], v[160:163], v[192:195], v[72:75]
	v_mfma_f32_16x16x32_bf16 v[72:75], v[164:167], v[196:199], v[72:75]
	v_mfma_f32_16x16x32_bf16 v[76:79], v[156:159], v[196:199], v[76:79]
	v_mfma_f32_16x16x32_bf16 v[76:79], v[152:155], v[192:195], v[76:79]
	s_setprio 0
	s_barrier
	s_add_i32 s44, 0, 0x1c000
	s_add_i32 s45, s71, s51
	v_add_u32_e32 v209, s44, v147
	v_lshl_add_u64 v[144:145], v[144:145], 0, s[12:13]
	s_mov_b32 m0, s45
	ds_read_b128 v[200:203], v209
	ds_read_b128 v[204:207], v209 offset:1024
	ds_read_b128 v[210:213], v209 offset:2048
	ds_read_b128 v[214:217], v209 offset:3072
	global_load_lds_dwordx4 v[144:145], off
	v_lshl_add_u64 v[144:145], v[218:219], 0, s[12:13]
	s_add_i32 m0, s45, 0x2000
	s_nop 0
	global_load_lds_dwordx4 v[144:145], off
	s_barrier
	s_waitcnt lgkmcnt(0)
	s_setprio 1
	s_waitcnt lgkmcnt(0)
	v_mfma_f32_16x16x32_bf16 v[116:119], v[200:203], v[168:171], v[116:119]
	v_mfma_f32_16x16x32_bf16 v[116:119], v[204:207], v[172:175], v[116:119]
	v_mfma_f32_16x16x32_bf16 v[112:115], v[214:217], v[172:175], v[112:115]
	v_mfma_f32_16x16x32_bf16 v[112:115], v[210:213], v[168:171], v[112:115]
	v_mfma_f32_16x16x32_bf16 v[96:99], v[210:213], v[176:179], v[96:99]
	v_mfma_f32_16x16x32_bf16 v[96:99], v[214:217], v[180:183], v[96:99]
	v_mfma_f32_16x16x32_bf16 v[100:103], v[204:207], v[180:183], v[100:103]
	v_mfma_f32_16x16x32_bf16 v[100:103], v[200:203], v[176:179], v[100:103]
	v_mfma_f32_16x16x32_bf16 v[84:87], v[200:203], v[184:187], v[84:87]
	v_mfma_f32_16x16x32_bf16 v[84:87], v[204:207], v[188:191], v[84:87]
	v_mfma_f32_16x16x32_bf16 v[80:83], v[214:217], v[188:191], v[80:83]
	v_mfma_f32_16x16x32_bf16 v[80:83], v[210:213], v[184:187], v[80:83]
	v_mfma_f32_16x16x32_bf16 v[64:67], v[210:213], v[192:195], v[64:67]
	v_mfma_f32_16x16x32_bf16 v[64:67], v[214:217], v[196:199], v[64:67]
	v_mfma_f32_16x16x32_bf16 v[68:71], v[204:207], v[196:199], v[68:71]
	v_mfma_f32_16x16x32_bf16 v[68:71], v[200:203], v[192:195], v[68:71]
	s_setprio 0
	s_mov_b32 m0, s61
	v_lshl_add_u64 v[144:145], v[220:221], 0, s[12:13]
	s_barrier
	ds_read_b128 v[168:171], v150 offset:49152
	ds_read_b128 v[172:175], v150 offset:50176
	ds_read_b128 v[176:179], v150 offset:51200
	ds_read_b128 v[180:183], v150 offset:52224
	ds_read_b128 v[184:187], v150 offset:53248
	ds_read_b128 v[188:191], v150 offset:54272
	ds_read_b128 v[192:195], v150 offset:55296
	ds_read_b128 v[196:199], v150 offset:56320
	global_load_lds_dwordx4 v[144:145], off
	v_lshl_add_u64 v[144:145], v[222:223], 0, s[12:13]
	s_mov_b32 m0, s62
	s_nop 0
	global_load_lds_dwordx4 v[144:145], off
	s_barrier
; __device__ __forceinline__ unsigned cvt_pk_bf16(float lo, float hi) { unsigned r; asm volatile("v_cvt_pk_bf16_f32 %0, %1, %2" : "=v"(r) : "v"(lo), "v"(hi)); return r; }
; #define PG8_STAGE(bufoff, gbase, voff) do { _Pragma("unroll") for (int _i = 0; _i < 2; ++_i) \
;         __builtin_amdgcn_global_load_lds((const unsigned*)((const char*)(gbase) + (voff)[_i]), (LAS unsigned*)(lds + (bufoff) + ldsw + _i * 8192), 16, 0, 0); } while (0)
; #define PG8_MMA(ai, bj, At, Bt) do { __builtin_amdgcn_s_setprio(1); _Pragma("unroll") for (int m = 0; m < 4; ++m) _Pragma("unroll") for (int n = 0; n < 2; ++n) _Pragma("unroll") for (int k = 0; k < 2; ++k) \
;         acc[ai][bj][m][n] = __builtin_amdgcn_mfma_f32_16x16x32_bf16(Bt[n][k], At[m][k], acc[ai][bj][m][n], 0, 0, 0); __builtin_amdgcn_s_setprio(0); } while (0)
; #define PG8_WAIT_V(n) asm volatile("s_waitcnt vmcnt(" #n ")" ::: "memory")
; #define PG8_WAIT_L(n) asm volatile("s_waitcnt lgkmcnt(" #n ")" ::: "memory")
; #define PG8_BAR __builtin_amdgcn_s_barrier()
; #define PG8_SCHED __builtin_amdgcn_sched_barrier(0)
; template <class Epi, class Ptrs>
; __device__ __forceinline__ void gemm_phase(LAS unsigned char* lds, const int K, const StaticOrder& S, const Ptrs& P, const Epi& E) {
;     ...
;             PG8_BAR; PG8_WAIT_L(0); PG8_MMA(1, 0, At, B0); PG8_BAR; PG8_SCHED;
;             PG8_STAGE(PG8_SB(1, 1), b3 + hstep, voffB);
;             PG8_WAIT_V(6); PG8_BAR; PG8_MMA(1, 1, At, B1); PG8_BAR;
;     __device__ __forceinline__ void operator()(const f32x4 (&acc)[2][2][4][2], const Unit& u, int ui, int wr, int wc, int fr, int fq) const {
;     ...
; #pragma unroll
;         for (int ai = 0; ai < 2; ++ai)
; #pragma unroll
;             for (int m = 0; m < 4; ++m) { bf16_t* rowp = hid + (size_t)(row0 + ai * 128 + m * 16) * DFF + col0;
; #pragma unroll
;                 for (int bj = 0; bj < 2; ++bj) { f32x4 v0 = acc[ai][bj][m][0], v1 = acc[ai][bj][m][1];
; #pragma unroll
;                     for (int j = 0; j < 4; ++j) { const float a = fmaxf(v0[j], 0.f), b = fmaxf(v1[j], 0.f); v0[j] = a * a; v1[j] = b * b; }
;                     u32x4 w; w.x = cvt_pk_bf16(v0[0], v0[1]); w.y = cvt_pk_bf16(v0[2], v0[3]); w.z = cvt_pk_bf16(v1[0], v1[1]); w.w = cvt_pk_bf16(v1[2], v1[3]);
;                     *(u32x4*)(rowp + bj * 128) = w; } }
	s_waitcnt lgkmcnt(0)
	s_setprio 1
	s_waitcnt lgkmcnt(0)
	v_mfma_f32_16x16x32_bf16 v[60:63], v[152:155], v[168:171], v[60:63]
	v_mfma_f32_16x16x32_bf16 v[60:63], v[156:159], v[172:175], v[60:63]
	v_mfma_f32_16x16x32_bf16 v[56:59], v[164:167], v[172:175], v[56:59]
	v_mfma_f32_16x16x32_bf16 v[56:59], v[160:163], v[168:171], v[56:59]
	v_mfma_f32_16x16x32_bf16 v[40:43], v[160:163], v[176:179], v[40:43]
	v_mfma_f32_16x16x32_bf16 v[40:43], v[164:167], v[180:183], v[40:43]
	v_mfma_f32_16x16x32_bf16 v[44:47], v[156:159], v[180:183], v[44:47]
	v_mfma_f32_16x16x32_bf16 v[44:47], v[152:155], v[176:179], v[44:47]
	v_mfma_f32_16x16x32_bf16 v[28:31], v[152:155], v[184:187], v[28:31]
	v_mfma_f32_16x16x32_bf16 v[28:31], v[156:159], v[188:191], v[28:31]
	v_mfma_f32_16x16x32_bf16 v[24:27], v[164:167], v[188:191], v[24:27]
	v_mfma_f32_16x16x32_bf16 v[24:27], v[160:163], v[184:187], v[24:27]
	v_mfma_f32_16x16x32_bf16 v[8:11], v[160:163], v[192:195], v[8:11]
	v_mfma_f32_16x16x32_bf16 v[8:11], v[164:167], v[196:199], v[8:11]
	v_mfma_f32_16x16x32_bf16 v[12:15], v[156:159], v[196:199], v[12:15]
	v_mfma_f32_16x16x32_bf16 v[12:15], v[152:155], v[192:195], v[12:15]
	s_setprio 0
	s_barrier
	s_add_u32 s42, s42, 0x40080
	s_addc_u32 s43, s43, 0
	s_add_i32 s44, s44, s51
	v_lshl_add_u64 v[144:145], s[42:43], 0, v[130:131]
	s_mov_b32 m0, s44
	s_nop 0
	global_load_lds_dwordx4 v[144:145], off
	v_lshl_add_u64 v[144:145], s[42:43], 0, v[134:135]
	s_add_i32 m0, s44, 0x2000
	s_nop 0
	global_load_lds_dwordx4 v[144:145], off
	s_waitcnt vmcnt(6)
	s_barrier
	s_setprio 1
	v_mfma_f32_16x16x32_bf16 v[52:55], v[200:203], v[168:171], v[52:55]
	v_mfma_f32_16x16x32_bf16 v[52:55], v[204:207], v[172:175], v[52:55]
	v_mfma_f32_16x16x32_bf16 v[48:51], v[214:217], v[172:175], v[48:51]
	v_mfma_f32_16x16x32_bf16 v[48:51], v[210:213], v[168:171], v[48:51]
	v_mfma_f32_16x16x32_bf16 v[32:35], v[210:213], v[176:179], v[32:35]
	v_mfma_f32_16x16x32_bf16 v[32:35], v[214:217], v[180:183], v[32:35]
	v_mfma_f32_16x16x32_bf16 v[36:39], v[204:207], v[180:183], v[36:39]
	v_mfma_f32_16x16x32_bf16 v[36:39], v[200:203], v[176:179], v[36:39]
	v_mfma_f32_16x16x32_bf16 v[20:23], v[200:203], v[184:187], v[20:23]
	v_mfma_f32_16x16x32_bf16 v[20:23], v[204:207], v[188:191], v[20:23]
	v_mfma_f32_16x16x32_bf16 v[16:19], v[214:217], v[188:191], v[16:19]
	v_mfma_f32_16x16x32_bf16 v[16:19], v[210:213], v[184:187], v[16:19]
	v_mfma_f32_16x16x32_bf16 v[0:3], v[210:213], v[192:195], v[0:3]
	v_mfma_f32_16x16x32_bf16 v[0:3], v[214:217], v[196:199], v[0:3]
	v_mfma_f32_16x16x32_bf16 v[4:7], v[204:207], v[196:199], v[4:7]
	v_mfma_f32_16x16x32_bf16 v[4:7], v[200:203], v[192:195], v[4:7]
	s_setprio 0
	s_add_i32 s70, s70, 2
	s_add_u32 s40, s40, 0x100
	s_addc_u32 s41, s41, 0
	s_add_u32 s23, s23, 0x100
	s_addc_u32 s25, s25, 0
	s_cmp_gt_u32 s70, 13
	s_barrier
	s_cbranch_scc0 .LBB0_433
	v_lshl_add_u32 v152, s38, 8, v146
	v_max_f32_e32 v120, v120, v120
	v_ashrrev_i32_e32 v153, 31, v152
	v_max_f32_e32 v120, 0, v120
	v_max_f32_e32 v121, v121, v121
	v_max_f32_e32 v122, v122, v122
	v_lshl_or_b32 v144, s69, 8, v148
	v_lshlrev_b64 v[154:155], 13, v[152:153]
	v_mul_f32_e32 v153, v120, v120
	v_max_f32_e32 v120, v125, v125
	v_max_f32_e32 v121, 0, v121
	v_max_f32_e32 v122, 0, v122
	v_ashrrev_i32_e32 v145, 31, v144
	v_max_f32_e32 v124, v124, v124
	v_max_f32_e32 v120, 0, v120
	v_mul_f32_e32 v125, v121, v121
	v_max_f32_e32 v121, v126, v126
	v_mul_f32_e32 v126, v122, v122
	v_max_f32_e32 v122, v127, v127
	v_max_f32_e32 v123, v123, v123
	v_lshl_add_u64 v[154:155], s[10:11], 0, v[154:155]
	v_lshlrev_b64 v[156:157], 1, v[144:145]
	v_max_f32_e32 v124, 0, v124
	v_mul_f32_e32 v120, v120, v120
	v_max_f32_e32 v121, 0, v121
	v_max_f32_e32 v122, 0, v122
	v_max_f32_e32 v123, 0, v123
	v_max_f32_e32 v112, v112, v112
	v_lshl_add_u64 v[144:145], v[154:155], 0, v[156:157]
	v_mul_f32_e32 v124, v124, v124
	v_mul_f32_e32 v121, v121, v121
	v_mul_f32_e32 v122, v122, v122
	v_mul_f32_e32 v123, v123, v123
	v_cvt_pk_bf16_f32 v120, v124, v120
	v_max_f32_e32 v112, 0, v112
	v_max_f32_e32 v113, v113, v113
	v_max_f32_e32 v114, v114, v114
	v_cvt_pk_bf16_f32 v121, v121, v122
	v_cvt_pk_bf16_f32 v122, v153, v125
	v_cvt_pk_bf16_f32 v123, v126, v123
	global_store_dwordx4 v[144:145], v[120:123], off
	v_max_f32_e32 v113, 0, v113
	v_max_f32_e32 v114, 0, v114
	v_mul_f32_e32 v120, v112, v112
	v_max_f32_e32 v112, v117, v117
	v_max_f32_e32 v116, v116, v116
	v_max_f32_e32 v112, 0, v112
	v_mul_f32_e32 v117, v113, v113
	v_max_f32_e32 v113, v118, v118
	v_mul_f32_e32 v118, v114, v114
	v_max_f32_e32 v114, v119, v119
	v_max_f32_e32 v115, v115, v115
	v_max_f32_e32 v116, 0, v116
	v_mul_f32_e32 v112, v112, v112
	v_max_f32_e32 v113, 0, v113
	v_max_f32_e32 v114, 0, v114
	v_max_f32_e32 v115, 0, v115
	v_mul_f32_e32 v116, v116, v116
	v_mul_f32_e32 v113, v113, v113
	v_mul_f32_e32 v114, v114, v114
	v_mul_f32_e32 v115, v115, v115
	v_cvt_pk_bf16_f32 v112, v116, v112
	v_max_f32_e32 v104, v104, v104
	v_cvt_pk_bf16_f32 v113, v113, v114
	v_cvt_pk_bf16_f32 v114, v120, v117
	v_cvt_pk_bf16_f32 v115, v118, v115
	global_store_dwordx4 v[144:145], v[112:115], off offset:256
	v_max_f32_e32 v104, 0, v104
	v_max_f32_e32 v105, v105, v105
	v_or_b32_e32 v112, 16, v152
	v_max_f32_e32 v106, v106, v106
	v_ashrrev_i32_e32 v113, 31, v112
	v_mul_f32_e32 v114, v104, v104
	v_max_f32_e32 v104, v109, v109
	v_max_f32_e32 v105, 0, v105
	v_max_f32_e32 v106, 0, v106
	v_lshlrev_b64 v[112:113], 13, v[112:113]
	v_max_f32_e32 v108, v108, v108
	v_max_f32_e32 v104, 0, v104
	v_mul_f32_e32 v109, v105, v105
	v_max_f32_e32 v105, v110, v110
	v_mul_f32_e32 v110, v106, v106
	v_max_f32_e32 v106, v111, v111
	v_max_f32_e32 v107, v107, v107
; __device__ __forceinline__ unsigned cvt_pk_bf16(float lo, float hi) { unsigned r; asm volatile("v_cvt_pk_bf16_f32 %0, %1, %2" : "=v"(r) : "v"(lo), "v"(hi)); return r; }
;     __device__ __forceinline__ void operator()(const f32x4 (&acc)[2][2][4][2], const Unit& u, int ui, int wr, int wc, int fr, int fq) const {
;     ...
; #pragma unroll
;         for (int ai = 0; ai < 2; ++ai)
; #pragma unroll
;             for (int m = 0; m < 4; ++m) { bf16_t* rowp = hid + (size_t)(row0 + ai * 128 + m * 16) * DFF + col0;
; #pragma unroll
;                 for (int bj = 0; bj < 2; ++bj) { f32x4 v0 = acc[ai][bj][m][0], v1 = acc[ai][bj][m][1];
; #pragma unroll
;                     for (int j = 0; j < 4; ++j) { const float a = fmaxf(v0[j], 0.f), b = fmaxf(v1[j], 0.f); v0[j] = a * a; v1[j] = b * b; }
;                     u32x4 w; w.x = cvt_pk_bf16(v0[0], v0[1]); w.y = cvt_pk_bf16(v0[2], v0[3]); w.z = cvt_pk_bf16(v1[0], v1[1]); w.w = cvt_pk_bf16(v1[2], v1[3]);
;                     *(u32x4*)(rowp + bj * 128) = w; } }
	v_lshl_add_u64 v[112:113], s[10:11], 0, v[112:113]
	v_max_f32_e32 v108, 0, v108
	v_mul_f32_e32 v104, v104, v104
	v_max_f32_e32 v105, 0, v105
	v_max_f32_e32 v106, 0, v106
	v_max_f32_e32 v107, 0, v107
	v_max_f32_e32 v96, v96, v96
	v_lshl_add_u64 v[112:113], v[112:113], 0, v[156:157]
	v_mul_f32_e32 v108, v108, v108
	v_mul_f32_e32 v105, v105, v105
	v_mul_f32_e32 v106, v106, v106
	v_mul_f32_e32 v107, v107, v107
	v_cvt_pk_bf16_f32 v104, v108, v104
	v_max_f32_e32 v96, 0, v96
	v_max_f32_e32 v97, v97, v97
	v_max_f32_e32 v98, v98, v98
	v_cvt_pk_bf16_f32 v105, v105, v106
	v_cvt_pk_bf16_f32 v106, v114, v109
	v_cvt_pk_bf16_f32 v107, v110, v107
	global_store_dwordx4 v[112:113], v[104:107], off
	v_max_f32_e32 v97, 0, v97
	v_max_f32_e32 v98, 0, v98
	v_mul_f32_e32 v104, v96, v96
	v_max_f32_e32 v96, v101, v101
	v_max_f32_e32 v100, v100, v100
	v_max_f32_e32 v96, 0, v96
	v_mul_f32_e32 v101, v97, v97
	v_max_f32_e32 v97, v102, v102
	v_mul_f32_e32 v102, v98, v98
	v_max_f32_e32 v98, v103, v103
	v_max_f32_e32 v99, v99, v99
	v_max_f32_e32 v100, 0, v100
	v_mul_f32_e32 v96, v96, v96
	v_max_f32_e32 v97, 0, v97
	v_max_f32_e32 v98, 0, v98
	v_max_f32_e32 v99, 0, v99
	v_mul_f32_e32 v100, v100, v100
	v_mul_f32_e32 v97, v97, v97
	v_mul_f32_e32 v98, v98, v98
	v_mul_f32_e32 v99, v99, v99
	v_cvt_pk_bf16_f32 v96, v100, v96
	v_max_f32_e32 v88, v88, v88
	v_cvt_pk_bf16_f32 v97, v97, v98
	v_cvt_pk_bf16_f32 v98, v104, v101
	v_cvt_pk_bf16_f32 v99, v102, v99
	global_store_dwordx4 v[112:113], v[96:99], off offset:256
	v_max_f32_e32 v88, 0, v88
	v_max_f32_e32 v89, v89, v89
	v_or_b32_e32 v96, 32, v152
	v_max_f32_e32 v90, v90, v90
	v_ashrrev_i32_e32 v97, 31, v96
	v_mul_f32_e32 v98, v88, v88
	v_max_f32_e32 v88, v93, v93
	v_max_f32_e32 v89, 0, v89
	v_max_f32_e32 v90, 0, v90
	v_lshlrev_b64 v[96:97], 13, v[96:97]
	v_max_f32_e32 v92, v92, v92
	v_max_f32_e32 v88, 0, v88
	v_mul_f32_e32 v93, v89, v89
	v_max_f32_e32 v89, v94, v94
	v_mul_f32_e32 v94, v90, v90
	v_max_f32_e32 v90, v95, v95
	v_max_f32_e32 v91, v91, v91
	v_lshl_add_u64 v[96:97], s[10:11], 0, v[96:97]
	v_max_f32_e32 v92, 0, v92
	v_mul_f32_e32 v88, v88, v88
	v_max_f32_e32 v89, 0, v89
	v_max_f32_e32 v90, 0, v90
	v_max_f32_e32 v91, 0, v91
	v_max_f32_e32 v80, v80, v80
	v_lshl_add_u64 v[96:97], v[96:97], 0, v[156:157]
	v_mul_f32_e32 v92, v92, v92
	v_mul_f32_e32 v89, v89, v89
	v_mul_f32_e32 v90, v90, v90
	v_mul_f32_e32 v91, v91, v91
	v_cvt_pk_bf16_f32 v88, v92, v88
	v_max_f32_e32 v80, 0, v80
	v_max_f32_e32 v81, v81, v81
	v_max_f32_e32 v82, v82, v82
	v_cvt_pk_bf16_f32 v89, v89, v90
	v_cvt_pk_bf16_f32 v90, v98, v93
	v_cvt_pk_bf16_f32 v91, v94, v91
	global_store_dwordx4 v[96:97], v[88:91], off
	v_max_f32_e32 v81, 0, v81
	v_max_f32_e32 v82, 0, v82
	v_mul_f32_e32 v88, v80, v80
	v_max_f32_e32 v80, v85, v85
	v_max_f32_e32 v84, v84, v84
	v_max_f32_e32 v80, 0, v80
	v_mul_f32_e32 v85, v81, v81
	v_max_f32_e32 v81, v86, v86
	v_mul_f32_e32 v86, v82, v82
	v_max_f32_e32 v82, v87, v87
	v_max_f32_e32 v83, v83, v83
	v_max_f32_e32 v84, 0, v84
	v_mul_f32_e32 v80, v80, v80
	v_max_f32_e32 v81, 0, v81
	v_max_f32_e32 v82, 0, v82
	v_max_f32_e32 v83, 0, v83
	v_mul_f32_e32 v84, v84, v84
	v_mul_f32_e32 v81, v81, v81
	v_mul_f32_e32 v82, v82, v82
	v_mul_f32_e32 v83, v83, v83
	v_cvt_pk_bf16_f32 v80, v84, v80
	v_max_f32_e32 v72, v72, v72
	v_cvt_pk_bf16_f32 v81, v81, v82
	v_cvt_pk_bf16_f32 v82, v88, v85
	v_cvt_pk_bf16_f32 v83, v86, v83
	global_store_dwordx4 v[96:97], v[80:83], off offset:256
	v_max_f32_e32 v72, 0, v72
	v_max_f32_e32 v73, v73, v73
	v_or_b32_e32 v80, 48, v152
	v_max_f32_e32 v74, v74, v74
	v_ashrrev_i32_e32 v81, 31, v80
	v_mul_f32_e32 v82, v72, v72
	v_max_f32_e32 v72, v77, v77
	v_max_f32_e32 v73, 0, v73
	v_max_f32_e32 v74, 0, v74
	v_lshlrev_b64 v[80:81], 13, v[80:81]
	v_max_f32_e32 v76, v76, v76
	v_max_f32_e32 v72, 0, v72
	v_mul_f32_e32 v77, v73, v73
	v_max_f32_e32 v73, v78, v78
	v_mul_f32_e32 v78, v74, v74
	v_max_f32_e32 v74, v79, v79
	v_max_f32_e32 v75, v75, v75
	v_lshl_add_u64 v[80:81], s[10:11], 0, v[80:81]
	v_max_f32_e32 v76, 0, v76
	v_mul_f32_e32 v72, v72, v72
	v_max_f32_e32 v73, 0, v73
	v_max_f32_e32 v74, 0, v74
	v_max_f32_e32 v75, 0, v75
	v_max_f32_e32 v64, v64, v64
	v_max_f32_e32 v65, v65, v65
	v_max_f32_e32 v66, v66, v66
	v_lshl_add_u64 v[80:81], v[80:81], 0, v[156:157]
	v_mul_f32_e32 v76, v76, v76
	v_mul_f32_e32 v73, v73, v73
	v_mul_f32_e32 v74, v74, v74
	v_mul_f32_e32 v75, v75, v75
	v_cvt_pk_bf16_f32 v72, v76, v72
	v_max_f32_e32 v64, 0, v64
	v_max_f32_e32 v65, 0, v65
	v_max_f32_e32 v66, 0, v66
	v_cvt_pk_bf16_f32 v73, v73, v74
	v_cvt_pk_bf16_f32 v74, v82, v77
	v_cvt_pk_bf16_f32 v75, v78, v75
	global_store_dwordx4 v[80:81], v[72:75], off
	v_max_f32_e32 v68, v68, v68
	v_max_f32_e32 v67, v67, v67
	v_mul_f32_e32 v72, v64, v64
	v_max_f32_e32 v64, v69, v69
	v_mul_f32_e32 v69, v65, v65
	v_max_f32_e32 v65, v70, v70
	v_mul_f32_e32 v70, v66, v66
	v_max_f32_e32 v66, v71, v71
	v_max_f32_e32 v64, 0, v64
	v_max_f32_e32 v65, 0, v65
	v_max_f32_e32 v66, 0, v66
	v_max_f32_e32 v68, 0, v68
	v_mul_f32_e32 v64, v64, v64
	v_mul_f32_e32 v65, v65, v65
	v_max_f32_e32 v67, 0, v67
	v_mul_f32_e32 v66, v66, v66
	v_max_f32_e32 v56, v56, v56
	v_mul_f32_e32 v68, v68, v68
	v_mul_f32_e32 v67, v67, v67
	v_cvt_pk_bf16_f32 v64, v68, v64
	v_cvt_pk_bf16_f32 v65, v65, v66
	v_cvt_pk_bf16_f32 v66, v72, v69
	v_max_f32_e32 v56, 0, v56
	v_max_f32_e32 v57, v57, v57
	v_max_f32_e32 v58, v58, v58
	v_cvt_pk_bf16_f32 v67, v70, v67
	global_store_dwordx4 v[80:81], v[64:67], off offset:256
	v_max_f32_e32 v60, v60, v60
	v_max_f32_e32 v57, 0, v57
	v_mul_f32_e32 v66, v56, v56
	v_max_f32_e32 v56, v61, v61
	v_max_f32_e32 v58, 0, v58
	v_max_f32_e32 v60, 0, v60
	v_max_f32_e32 v56, 0, v56
	v_mul_f32_e32 v61, v57, v57
; __device__ __forceinline__ unsigned cvt_pk_bf16(float lo, float hi) { unsigned r; asm volatile("v_cvt_pk_bf16_f32 %0, %1, %2" : "=v"(r) : "v"(lo), "v"(hi)); return r; }
;     __device__ __forceinline__ void operator()(const f32x4 (&acc)[2][2][4][2], const Unit& u, int ui, int wr, int wc, int fr, int fq) const {
;     ...
; #pragma unroll
;         for (int ai = 0; ai < 2; ++ai)
; #pragma unroll
;             for (int m = 0; m < 4; ++m) { bf16_t* rowp = hid + (size_t)(row0 + ai * 128 + m * 16) * DFF + col0;
; #pragma unroll
;                 for (int bj = 0; bj < 2; ++bj) { f32x4 v0 = acc[ai][bj][m][0], v1 = acc[ai][bj][m][1];
; #pragma unroll
;                     for (int j = 0; j < 4; ++j) { const float a = fmaxf(v0[j], 0.f), b = fmaxf(v1[j], 0.f); v0[j] = a * a; v1[j] = b * b; }
;                     u32x4 w; w.x = cvt_pk_bf16(v0[0], v0[1]); w.y = cvt_pk_bf16(v0[2], v0[3]); w.z = cvt_pk_bf16(v1[0], v1[1]); w.w = cvt_pk_bf16(v1[2], v1[3]);
;                     *(u32x4*)(rowp + bj * 128) = w; } }
	v_max_f32_e32 v57, v62, v62
	v_mul_f32_e32 v62, v58, v58
	v_max_f32_e32 v58, v63, v63
	v_mul_f32_e32 v60, v60, v60
	v_mul_f32_e32 v56, v56, v56
	v_max_f32_e32 v57, 0, v57
	v_max_f32_e32 v58, 0, v58
	v_max_f32_e32 v59, v59, v59
	v_mul_f32_e32 v57, v57, v57
	v_max_f32_e32 v59, 0, v59
	v_mul_f32_e32 v58, v58, v58
	v_cvt_pk_bf16_f32 v56, v60, v56
	v_add_co_u32_e32 v60, vcc, s65, v144
	v_max_f32_e32 v48, v48, v48
	v_max_f32_e32 v49, v49, v49
	v_max_f32_e32 v50, v50, v50
	v_mul_f32_e32 v59, v59, v59
	v_cvt_pk_bf16_f32 v57, v57, v58
	v_cvt_pk_bf16_f32 v58, v66, v61
	v_addc_co_u32_e32 v61, vcc, 0, v145, vcc
	v_max_f32_e32 v48, 0, v48
	v_max_f32_e32 v49, 0, v49
	v_max_f32_e32 v50, 0, v50
	v_cvt_pk_bf16_f32 v59, v62, v59
	global_store_dwordx4 v[60:61], v[56:59], off
	v_max_f32_e32 v52, v52, v52
	v_max_f32_e32 v51, v51, v51
	v_mul_f32_e32 v56, v48, v48
	v_max_f32_e32 v48, v53, v53
	v_mul_f32_e32 v53, v49, v49
	v_max_f32_e32 v49, v54, v54
	v_mul_f32_e32 v54, v50, v50
	v_max_f32_e32 v50, v55, v55
	v_max_f32_e32 v48, 0, v48
	v_max_f32_e32 v49, 0, v49
	v_max_f32_e32 v50, 0, v50
	v_max_f32_e32 v52, 0, v52
	v_mul_f32_e32 v48, v48, v48
	v_mul_f32_e32 v49, v49, v49
	v_max_f32_e32 v51, 0, v51
	v_mul_f32_e32 v50, v50, v50
	v_max_f32_e32 v40, v40, v40
	v_lshl_add_u64 v[64:65], v[144:145], 0, s[14:15]
	v_mul_f32_e32 v52, v52, v52
	v_mul_f32_e32 v51, v51, v51
	v_cvt_pk_bf16_f32 v48, v52, v48
	v_cvt_pk_bf16_f32 v49, v49, v50
	v_cvt_pk_bf16_f32 v50, v56, v53
	v_max_f32_e32 v40, 0, v40
	v_max_f32_e32 v41, v41, v41
	v_max_f32_e32 v42, v42, v42
	v_cvt_pk_bf16_f32 v51, v54, v51
	global_store_dwordx4 v[64:65], v[48:51], off offset:256
	v_max_f32_e32 v44, v44, v44
	v_max_f32_e32 v41, 0, v41
	v_mul_f32_e32 v50, v40, v40
	v_max_f32_e32 v40, v45, v45
	v_max_f32_e32 v42, 0, v42
	v_max_f32_e32 v44, 0, v44
	v_max_f32_e32 v40, 0, v40
	v_mul_f32_e32 v45, v41, v41
	v_max_f32_e32 v41, v46, v46
	v_mul_f32_e32 v46, v42, v42
	v_max_f32_e32 v42, v47, v47
	v_mul_f32_e32 v44, v44, v44
	v_mul_f32_e32 v40, v40, v40
	v_max_f32_e32 v41, 0, v41
	v_max_f32_e32 v42, 0, v42
	v_max_f32_e32 v43, v43, v43
	v_mul_f32_e32 v41, v41, v41
	v_max_f32_e32 v43, 0, v43
	v_mul_f32_e32 v42, v42, v42
	v_cvt_pk_bf16_f32 v40, v44, v40
	v_add_co_u32_e32 v44, vcc, s66, v144
	v_max_f32_e32 v32, v32, v32
	v_max_f32_e32 v33, v33, v33
	v_max_f32_e32 v34, v34, v34
	v_mul_f32_e32 v43, v43, v43
	v_cvt_pk_bf16_f32 v41, v41, v42
	v_cvt_pk_bf16_f32 v42, v50, v45
	v_addc_co_u32_e32 v45, vcc, 0, v145, vcc
	v_max_f32_e32 v32, 0, v32
	v_max_f32_e32 v33, 0, v33
	v_max_f32_e32 v34, 0, v34
	v_cvt_pk_bf16_f32 v43, v46, v43
	global_store_dwordx4 v[44:45], v[40:43], off
	v_max_f32_e32 v36, v36, v36
	v_max_f32_e32 v35, v35, v35
	v_mul_f32_e32 v40, v32, v32
	v_max_f32_e32 v32, v37, v37
	v_mul_f32_e32 v37, v33, v33
	v_max_f32_e32 v33, v38, v38
	v_mul_f32_e32 v38, v34, v34
	v_max_f32_e32 v34, v39, v39
	v_max_f32_e32 v32, 0, v32
	v_max_f32_e32 v33, 0, v33
	v_max_f32_e32 v34, 0, v34
	v_max_f32_e32 v36, 0, v36
	v_mul_f32_e32 v32, v32, v32
	v_mul_f32_e32 v33, v33, v33
	v_max_f32_e32 v35, 0, v35
	v_mul_f32_e32 v34, v34, v34
	v_max_f32_e32 v24, v24, v24
	v_lshl_add_u64 v[48:49], v[144:145], 0, s[16:17]
	v_mul_f32_e32 v36, v36, v36
	v_mul_f32_e32 v35, v35, v35
	v_cvt_pk_bf16_f32 v32, v36, v32
	v_cvt_pk_bf16_f32 v33, v33, v34
	v_cvt_pk_bf16_f32 v34, v40, v37
	v_max_f32_e32 v24, 0, v24
	v_max_f32_e32 v25, v25, v25
	v_max_f32_e32 v26, v26, v26
	v_cvt_pk_bf16_f32 v35, v38, v35
	global_store_dwordx4 v[48:49], v[32:35], off offset:256
	v_max_f32_e32 v28, v28, v28
	v_max_f32_e32 v25, 0, v25
	v_mul_f32_e32 v34, v24, v24
	v_max_f32_e32 v24, v29, v29
; __device__ __forceinline__ unsigned cvt_pk_bf16(float lo, float hi) { unsigned r; asm volatile("v_cvt_pk_bf16_f32 %0, %1, %2" : "=v"(r) : "v"(lo), "v"(hi)); return r; }
; #define PG8_WAIT_V(n) asm volatile("s_waitcnt vmcnt(" #n ")" ::: "memory")
; #define PG8_BAR __builtin_amdgcn_s_barrier()
; template <class Epi, class Ptrs>
; __device__ __forceinline__ void gemm_phase(LAS unsigned char* lds, const int K, const StaticOrder& S, const Ptrs& P, const Epi& E) {
;     ...
;         cur = nxt; cA = nA; cB = nB; ++ui;
;     }
;     PG8_WAIT_V(0);
;     if (wr == 0) PG8_BAR;
;     PG8_BAR;
;     __device__ __forceinline__ void operator()(const f32x4 (&acc)[2][2][4][2], const Unit& u, int ui, int wr, int wc, int fr, int fq) const {
;     ...
;             for (int m = 0; m < 4; ++m) { bf16_t* rowp = hid + (size_t)(row0 + ai * 128 + m * 16) * DFF + col0;
; #pragma unroll
;                 for (int bj = 0; bj < 2; ++bj) { f32x4 v0 = acc[ai][bj][m][0], v1 = acc[ai][bj][m][1];
; #pragma unroll
;                     for (int j = 0; j < 4; ++j) { const float a = fmaxf(v0[j], 0.f), b = fmaxf(v1[j], 0.f); v0[j] = a * a; v1[j] = b * b; }
;                     u32x4 w; w.x = cvt_pk_bf16(v0[0], v0[1]); w.y = cvt_pk_bf16(v0[2], v0[3]); w.z = cvt_pk_bf16(v1[0], v1[1]); w.w = cvt_pk_bf16(v1[2], v1[3]);
;                     *(u32x4*)(rowp + bj * 128) = w; } }
	v_max_f32_e32 v26, 0, v26
	v_max_f32_e32 v28, 0, v28
	v_max_f32_e32 v24, 0, v24
	v_mul_f32_e32 v29, v25, v25
	v_max_f32_e32 v25, v30, v30
	v_mul_f32_e32 v30, v26, v26
	v_max_f32_e32 v26, v31, v31
	v_mul_f32_e32 v28, v28, v28
	v_mul_f32_e32 v24, v24, v24
	v_max_f32_e32 v25, 0, v25
	v_max_f32_e32 v26, 0, v26
	v_max_f32_e32 v27, v27, v27
	v_mul_f32_e32 v25, v25, v25
	v_max_f32_e32 v27, 0, v27
	v_mul_f32_e32 v26, v26, v26
	v_cvt_pk_bf16_f32 v24, v28, v24
	v_add_co_u32_e32 v28, vcc, s67, v144
	v_max_f32_e32 v16, v16, v16
	v_max_f32_e32 v17, v17, v17
	v_max_f32_e32 v18, v18, v18
	v_mul_f32_e32 v27, v27, v27
	v_cvt_pk_bf16_f32 v25, v25, v26
	v_cvt_pk_bf16_f32 v26, v34, v29
	v_addc_co_u32_e32 v29, vcc, 0, v145, vcc
	v_max_f32_e32 v16, 0, v16
	v_max_f32_e32 v17, 0, v17
	v_max_f32_e32 v18, 0, v18
	v_cvt_pk_bf16_f32 v27, v30, v27
	global_store_dwordx4 v[28:29], v[24:27], off
	v_max_f32_e32 v20, v20, v20
	v_max_f32_e32 v19, v19, v19
	v_mul_f32_e32 v24, v16, v16
	v_max_f32_e32 v16, v21, v21
	v_mul_f32_e32 v21, v17, v17
	v_max_f32_e32 v17, v22, v22
	v_mul_f32_e32 v22, v18, v18
	v_max_f32_e32 v18, v23, v23
	v_max_f32_e32 v16, 0, v16
	v_max_f32_e32 v17, 0, v17
	v_max_f32_e32 v18, 0, v18
	v_max_f32_e32 v20, 0, v20
	v_mul_f32_e32 v16, v16, v16
	v_mul_f32_e32 v17, v17, v17
	v_max_f32_e32 v19, 0, v19
	v_mul_f32_e32 v18, v18, v18
	v_max_f32_e32 v8, v8, v8
	v_lshl_add_u64 v[32:33], v[144:145], 0, s[18:19]
	v_mul_f32_e32 v20, v20, v20
	v_mul_f32_e32 v19, v19, v19
	v_cvt_pk_bf16_f32 v16, v20, v16
	v_cvt_pk_bf16_f32 v17, v17, v18
	v_cvt_pk_bf16_f32 v18, v24, v21
	v_max_f32_e32 v8, 0, v8
	v_max_f32_e32 v9, v9, v9
	v_max_f32_e32 v10, v10, v10
	v_cvt_pk_bf16_f32 v19, v22, v19
	global_store_dwordx4 v[32:33], v[16:19], off offset:256
	v_max_f32_e32 v12, v12, v12
	v_max_f32_e32 v9, 0, v9
	v_mul_f32_e32 v18, v8, v8
	v_max_f32_e32 v8, v13, v13
	v_max_f32_e32 v10, 0, v10
	v_max_f32_e32 v12, 0, v12
	v_max_f32_e32 v8, 0, v8
	v_mul_f32_e32 v13, v9, v9
	v_max_f32_e32 v9, v14, v14
	v_mul_f32_e32 v14, v10, v10
	v_max_f32_e32 v10, v15, v15
	v_mul_f32_e32 v12, v12, v12
	v_mul_f32_e32 v8, v8, v8
	v_max_f32_e32 v9, 0, v9
	v_max_f32_e32 v10, 0, v10
	v_max_f32_e32 v11, v11, v11
	v_mul_f32_e32 v9, v9, v9
	v_max_f32_e32 v11, 0, v11
	v_mul_f32_e32 v10, v10, v10
	v_cvt_pk_bf16_f32 v8, v12, v8
	v_add_co_u32_e32 v12, vcc, s68, v144
	v_max_f32_e32 v0, v0, v0
	v_max_f32_e32 v1, v1, v1
	v_max_f32_e32 v2, v2, v2
	v_mul_f32_e32 v11, v11, v11
	v_cvt_pk_bf16_f32 v9, v9, v10
	v_cvt_pk_bf16_f32 v10, v18, v13
	v_addc_co_u32_e32 v13, vcc, 0, v145, vcc
	v_max_f32_e32 v0, 0, v0
	v_max_f32_e32 v1, 0, v1
	v_max_f32_e32 v2, 0, v2
	v_cvt_pk_bf16_f32 v11, v14, v11
	global_store_dwordx4 v[12:13], v[8:11], off
	v_max_f32_e32 v3, v3, v3
	v_max_f32_e32 v4, v4, v4
	v_mul_f32_e32 v8, v0, v0
	v_max_f32_e32 v0, v5, v5
	v_mul_f32_e32 v5, v1, v1
	v_max_f32_e32 v1, v6, v6
	v_mul_f32_e32 v6, v2, v2
	v_max_f32_e32 v2, v7, v7
	v_max_f32_e32 v0, 0, v0
	v_max_f32_e32 v1, 0, v1
	v_max_f32_e32 v2, 0, v2
	v_max_f32_e32 v3, 0, v3
	v_lshl_add_u64 v[16:17], v[144:145], 0, s[20:21]
	v_max_f32_e32 v4, 0, v4
	v_mul_f32_e32 v0, v0, v0
	v_mul_f32_e32 v1, v1, v1
	v_mul_f32_e32 v2, v2, v2
	v_mul_f32_e32 v3, v3, v3
	s_and_b64 vcc, exec, s[4:5]
	s_mov_b32 s69, s22
	s_mov_b32 s38, s24
	s_mov_b64 s[40:41], s[0:1]
	s_mov_b64 s[42:43], s[36:37]
	v_mul_f32_e32 v4, v4, v4
	v_cvt_pk_bf16_f32 v0, v4, v0
	v_cvt_pk_bf16_f32 v1, v1, v2
	v_cvt_pk_bf16_f32 v2, v8, v5
	v_cvt_pk_bf16_f32 v3, v6, v3
	global_store_dwordx4 v[16:17], v[0:3], off offset:256
	s_cbranch_vccz .LBB0_428
	s_waitcnt vmcnt(0)
	s_cmpk_gt_u32 s46, 0xff
	s_cbranch_scc1 .LBB0_437
	s_barrier

; #define PG8_STAGE(bufoff, gbase, voff) do { _Pragma("unroll") for (int _i = 0; _i < 2; ++_i) \
;         __builtin_amdgcn_global_load_lds((const unsigned*)((const char*)(gbase) + (voff)[_i]), (LAS unsigned*)(lds + (bufoff) + ldsw + _i * 8192), 16, 0, 0); } while (0)
; #define PG8_LDA(dst, b, h) do { _Pragma("unroll") for (int m = 0; m < 4; ++m) _Pragma("unroll") for (int k = 0; k < 2; ++k) dst[m][k] = *(const LAS bf16x8*)(lds + PG8_SA(b, h) + aoff + m * 2048 + k * 1024); } while (0)
; #define PG8_LDB(dst, b, h) do { _Pragma("unroll") for (int n = 0; n < 2; ++n) _Pragma("unroll") for (int k = 0; k < 2; ++k) dst[n][k] = *(const LAS bf16x8*)(lds + PG8_SB(b, h) + boff + n * 2048 + k * 1024); } while (0)
; #define PG8_MMA(ai, bj, At, Bt) do { __builtin_amdgcn_s_setprio(1); _Pragma("unroll") for (int m = 0; m < 4; ++m) _Pragma("unroll") for (int n = 0; n < 2; ++n) _Pragma("unroll") for (int k = 0; k < 2; ++k) \
;         acc[ai][bj][m][n] = __builtin_amdgcn_mfma_f32_16x16x32_bf16(Bt[n][k], At[m][k], acc[ai][bj][m][n], 0, 0, 0); __builtin_amdgcn_s_setprio(0); } while (0)
; #define PG8_WAIT_L(n) asm volatile("s_waitcnt lgkmcnt(" #n ")" ::: "memory")
; #define PG8_BAR __builtin_amdgcn_s_barrier()
; #define PG8_SCHED __builtin_amdgcn_sched_barrier(0)
; template <class Epi, class Ptrs>
; __device__ __forceinline__ void gemm_phase(LAS unsigned char* lds, const int K, const StaticOrder& S, const Ptrs& P, const Epi& E) {
;     ...
;         for (int t = 0; t < nt; t += 2) {
;             const bool last = (t == nt - 2);
;             const char* a1 = cA + (size_t)(t + 1) * kstep;
;             const char* a2 = last ? nA : cA + (size_t)(t + 2) * kstep; const char* b2 = last ? nB : cB + (size_t)(t + 2) * kstep;
;             const char* a3 = a2 + kstep; const char* b3 = b2 + kstep;
;             PG8_LDB(B0, 0, 0); PG8_SCHED; PG8_LDA(At, 0, 0); PG8_STAGE(PG8_SA(1, 1), a1 + hstep, voffA);
;             PG8_WAIT_L(8); PG8_BAR; PG8_WAIT_L(0); PG8_MMA(0, 0, At, B0); PG8_BAR; PG8_SCHED;
;             PG8_LDB(B1, 0, 1); PG8_STAGE(PG8_SB(0, 0), b2, voffB);
;             PG8_BAR; PG8_WAIT_L(0); PG8_MMA(0, 1, At, B1); PG8_BAR;
;             PG8_LDA(At, 0, 1); PG8_STAGE(PG8_SA(0, 0), a2, voffA);
;             PG8_BAR; PG8_WAIT_L(0); PG8_MMA(1, 0, At, B0); PG8_BAR; PG8_SCHED;
.LBB0_522:
	ds_read_b128 v[128:131], v193
	ds_read_b128 v[132:135], v193 offset:1024
	ds_read_b128 v[136:139], v193 offset:2048
	ds_read_b128 v[140:143], v193 offset:3072
	s_add_u32 s22, s20, 0xfff00080
	s_addc_u32 s23, s21, -1
	s_cmp_eq_u32 s46, 60
	s_cselect_b32 s25, s5, s23
	s_cselect_b32 s24, s4, s22
	s_cselect_b32 s23, s15, s13
	s_cselect_b32 s22, s14, s11
	v_lshl_add_u64 v[184:185], s[20:21], 0, v[168:169]
	s_add_i32 m0, s17, 0xc000
	ds_read_b128 v[144:147], v194
	ds_read_b128 v[148:151], v194 offset:1024
	ds_read_b128 v[152:155], v194 offset:2048
	ds_read_b128 v[156:159], v194 offset:3072
	ds_read_b128 v[176:179], v194 offset:4096
	ds_read_b128 v[180:183], v194 offset:5120
	ds_read_b128 v[196:199], v194 offset:6144
	ds_read_b128 v[200:203], v194 offset:7168
	global_load_lds_dwordx4 v[184:185], off
	v_lshl_add_u64 v[184:185], s[20:21], 0, v[170:171]
	s_add_i32 m0, s17, 0xe000
	s_nop 0
	global_load_lds_dwordx4 v[184:185], off
	s_waitcnt lgkmcnt(8)
	s_barrier
	s_waitcnt lgkmcnt(0)
	s_setprio 1
	s_waitcnt lgkmcnt(0)
	v_mfma_f32_16x16x32_bf16 v[124:127], v[128:131], v[144:147], v[124:127]
	v_mfma_f32_16x16x32_bf16 v[124:127], v[132:135], v[148:151], v[124:127]
	v_mfma_f32_16x16x32_bf16 v[120:123], v[140:143], v[148:151], v[120:123]
	v_mfma_f32_16x16x32_bf16 v[120:123], v[136:139], v[144:147], v[120:123]
	v_mfma_f32_16x16x32_bf16 v[104:107], v[136:139], v[152:155], v[104:107]
	v_mfma_f32_16x16x32_bf16 v[104:107], v[140:143], v[156:159], v[104:107]
	v_mfma_f32_16x16x32_bf16 v[112:115], v[132:135], v[156:159], v[112:115]
	v_mfma_f32_16x16x32_bf16 v[112:115], v[128:131], v[152:155], v[112:115]
	v_mfma_f32_16x16x32_bf16 v[92:95], v[128:131], v[176:179], v[92:95]
	v_mfma_f32_16x16x32_bf16 v[92:95], v[132:135], v[180:183], v[92:95]
	v_mfma_f32_16x16x32_bf16 v[88:91], v[140:143], v[180:183], v[88:91]
	v_mfma_f32_16x16x32_bf16 v[88:91], v[136:139], v[176:179], v[88:91]
	v_mfma_f32_16x16x32_bf16 v[72:75], v[136:139], v[196:199], v[72:75]
	v_mfma_f32_16x16x32_bf16 v[72:75], v[140:143], v[200:203], v[72:75]
	v_mfma_f32_16x16x32_bf16 v[76:79], v[132:135], v[200:203], v[76:79]
	v_mfma_f32_16x16x32_bf16 v[76:79], v[128:131], v[196:199], v[76:79]
	s_setprio 0
	s_barrier
	s_add_i32 s47, s42, s34
	v_lshl_add_u64 v[184:185], s[22:23], 0, v[162:163]
	s_mov_b32 m0, s47
	ds_read_b128 v[204:207], v195
	ds_read_b128 v[208:211], v195 offset:1024
	ds_read_b128 v[212:215], v195 offset:2048
	ds_read_b128 v[216:219], v195 offset:3072
	global_load_lds_dwordx4 v[184:185], off
	v_lshl_add_u64 v[220:221], s[22:23], 0, v[166:167]
	s_add_i32 m0, s47, 0x2000
	s_nop 0
	global_load_lds_dwordx4 v[220:221], off
	s_barrier
	s_waitcnt lgkmcnt(0)
	s_setprio 1
	s_waitcnt lgkmcnt(0)
	v_mfma_f32_16x16x32_bf16 v[116:119], v[204:207], v[144:147], v[116:119]
	v_mfma_f32_16x16x32_bf16 v[116:119], v[208:211], v[148:151], v[116:119]
	v_mfma_f32_16x16x32_bf16 v[108:111], v[216:219], v[148:151], v[108:111]
	v_mfma_f32_16x16x32_bf16 v[108:111], v[212:215], v[144:147], v[108:111]
	v_mfma_f32_16x16x32_bf16 v[96:99], v[212:215], v[152:155], v[96:99]
	v_mfma_f32_16x16x32_bf16 v[96:99], v[216:219], v[156:159], v[96:99]
	v_mfma_f32_16x16x32_bf16 v[100:103], v[208:211], v[156:159], v[100:103]
	v_mfma_f32_16x16x32_bf16 v[100:103], v[204:207], v[152:155], v[100:103]
	v_mfma_f32_16x16x32_bf16 v[84:87], v[204:207], v[176:179], v[84:87]
	v_mfma_f32_16x16x32_bf16 v[84:87], v[208:211], v[180:183], v[84:87]
	v_mfma_f32_16x16x32_bf16 v[80:83], v[216:219], v[180:183], v[80:83]
	v_mfma_f32_16x16x32_bf16 v[80:83], v[212:215], v[176:179], v[80:83]
	v_mfma_f32_16x16x32_bf16 v[64:67], v[212:215], v[196:199], v[64:67]
	v_mfma_f32_16x16x32_bf16 v[64:67], v[216:219], v[200:203], v[64:67]
	v_mfma_f32_16x16x32_bf16 v[68:71], v[208:211], v[200:203], v[68:71]
	v_mfma_f32_16x16x32_bf16 v[68:71], v[204:207], v[196:199], v[68:71]
	s_setprio 0
	s_mov_b32 m0, s17
	v_lshl_add_u64 v[222:223], s[24:25], 0, v[160:161]
	s_barrier
	ds_read_b128 v[144:147], v194 offset:16384
	ds_read_b128 v[148:151], v194 offset:17408
	ds_read_b128 v[152:155], v194 offset:18432
	ds_read_b128 v[156:159], v194 offset:19456
	ds_read_b128 v[176:179], v194 offset:20480
	ds_read_b128 v[180:183], v194 offset:21504
	ds_read_b128 v[196:199], v194 offset:22528
	ds_read_b128 v[200:203], v194 offset:23552
	global_load_lds_dwordx4 v[222:223], off
	v_lshl_add_u64 v[224:225], s[24:25], 0, v[164:165]
	s_mov_b32 m0, s19
	s_nop 0
	global_load_lds_dwordx4 v[224:225], off
	s_barrier
	s_waitcnt lgkmcnt(0)
	s_setprio 1
	s_waitcnt lgkmcnt(0)
	v_mfma_f32_16x16x32_bf16 v[60:63], v[128:131], v[144:147], v[60:63]
	v_mfma_f32_16x16x32_bf16 v[60:63], v[132:135], v[148:151], v[60:63]
	v_mfma_f32_16x16x32_bf16 v[56:59], v[140:143], v[148:151], v[56:59]
	v_mfma_f32_16x16x32_bf16 v[56:59], v[136:139], v[144:147], v[56:59]
	v_mfma_f32_16x16x32_bf16 v[40:43], v[136:139], v[152:155], v[40:43]
	v_mfma_f32_16x16x32_bf16 v[40:43], v[140:143], v[156:159], v[40:43]
	v_mfma_f32_16x16x32_bf16 v[48:51], v[132:135], v[156:159], v[48:51]
	v_mfma_f32_16x16x32_bf16 v[48:51], v[128:131], v[152:155], v[48:51]
	v_mfma_f32_16x16x32_bf16 v[32:35], v[128:131], v[176:179], v[32:35]
	v_mfma_f32_16x16x32_bf16 v[32:35], v[132:135], v[180:183], v[32:35]
	v_mfma_f32_16x16x32_bf16 v[24:27], v[140:143], v[180:183], v[24:27]
	v_mfma_f32_16x16x32_bf16 v[24:27], v[136:139], v[176:179], v[24:27]
	v_mfma_f32_16x16x32_bf16 v[8:11], v[136:139], v[196:199], v[8:11]
	v_mfma_f32_16x16x32_bf16 v[8:11], v[140:143], v[200:203], v[8:11]
	v_mfma_f32_16x16x32_bf16 v[16:19], v[132:135], v[200:203], v[16:19]
	v_mfma_f32_16x16x32_bf16 v[16:19], v[128:131], v[196:199], v[16:19]
	s_setprio 0
	s_barrier
; #define PG8_STAGE(bufoff, gbase, voff) do { _Pragma("unroll") for (int _i = 0; _i < 2; ++_i) \
;         __builtin_amdgcn_global_load_lds((const unsigned*)((const char*)(gbase) + (voff)[_i]), (LAS unsigned*)(lds + (bufoff) + ldsw + _i * 8192), 16, 0, 0); } while (0)
; #define PG8_LDA(dst, b, h) do { _Pragma("unroll") for (int m = 0; m < 4; ++m) _Pragma("unroll") for (int k = 0; k < 2; ++k) dst[m][k] = *(const LAS bf16x8*)(lds + PG8_SA(b, h) + aoff + m * 2048 + k * 1024); } while (0)
; #define PG8_LDB(dst, b, h) do { _Pragma("unroll") for (int n = 0; n < 2; ++n) _Pragma("unroll") for (int k = 0; k < 2; ++k) dst[n][k] = *(const LAS bf16x8*)(lds + PG8_SB(b, h) + boff + n * 2048 + k * 1024); } while (0)
; #define PG8_MMA(ai, bj, At, Bt) do { __builtin_amdgcn_s_setprio(1); _Pragma("unroll") for (int m = 0; m < 4; ++m) _Pragma("unroll") for (int n = 0; n < 2; ++n) _Pragma("unroll") for (int k = 0; k < 2; ++k) \
;         acc[ai][bj][m][n] = __builtin_amdgcn_mfma_f32_16x16x32_bf16(Bt[n][k], At[m][k], acc[ai][bj][m][n], 0, 0, 0); __builtin_amdgcn_s_setprio(0); } while (0)
; #define PG8_WAIT_V(n) asm volatile("s_waitcnt vmcnt(" #n ")" ::: "memory")
; #define PG8_WAIT_L(n) asm volatile("s_waitcnt lgkmcnt(" #n ")" ::: "memory")
; #define PG8_BAR __builtin_amdgcn_s_barrier()
; #define PG8_SCHED __builtin_amdgcn_sched_barrier(0)
; template <class Epi, class Ptrs>
; __device__ __forceinline__ void gemm_phase(LAS unsigned char* lds, const int K, const StaticOrder& S, const Ptrs& P, const Epi& E) {
;     ...
;             PG8_STAGE(PG8_SB(0, 1), b2 + hstep, voffB);
;             PG8_WAIT_V(6); PG8_BAR; PG8_MMA(1, 1, At, B1); PG8_BAR;
;             PG8_LDB(B0, 1, 0); PG8_SCHED; PG8_LDA(At, 1, 0); PG8_STAGE(PG8_SA(0, 1), a2 + hstep, voffA);
;             PG8_WAIT_L(8); PG8_BAR; PG8_WAIT_L(0); PG8_MMA(0, 0, At, B0); PG8_BAR; PG8_SCHED;
;             PG8_LDB(B1, 1, 1); PG8_STAGE(PG8_SB(1, 0), b3, voffB);
;             PG8_BAR; PG8_WAIT_L(0); PG8_MMA(0, 1, At, B1); PG8_BAR;
;             PG8_LDA(At, 1, 1); PG8_STAGE(PG8_SA(1, 0), a3, voffA);
	s_add_u32 s48, s22, 0x100000
	s_addc_u32 s49, s23, 0
	s_add_i32 s47, s43, s34
	v_lshl_add_u64 v[128:129], s[48:49], 0, v[162:163]
	s_mov_b32 m0, s47
	s_nop 0
	global_load_lds_dwordx4 v[128:129], off
	v_lshl_add_u64 v[128:129], s[48:49], 0, v[166:167]
	s_add_i32 m0, s47, 0x2000
	s_nop 0
	global_load_lds_dwordx4 v[128:129], off
	s_waitcnt vmcnt(6)
	s_barrier
	s_setprio 1
	v_mfma_f32_16x16x32_bf16 v[52:55], v[204:207], v[144:147], v[52:55]
	v_mfma_f32_16x16x32_bf16 v[52:55], v[208:211], v[148:151], v[52:55]
	v_mfma_f32_16x16x32_bf16 v[44:47], v[216:219], v[148:151], v[44:47]
	v_mfma_f32_16x16x32_bf16 v[44:47], v[212:215], v[144:147], v[44:47]
	v_mfma_f32_16x16x32_bf16 v[28:31], v[212:215], v[152:155], v[28:31]
	v_mfma_f32_16x16x32_bf16 v[28:31], v[216:219], v[156:159], v[28:31]
	v_mfma_f32_16x16x32_bf16 v[36:39], v[208:211], v[156:159], v[36:39]
	v_mfma_f32_16x16x32_bf16 v[36:39], v[204:207], v[152:155], v[36:39]
	v_mfma_f32_16x16x32_bf16 v[20:23], v[204:207], v[176:179], v[20:23]
	v_mfma_f32_16x16x32_bf16 v[20:23], v[208:211], v[180:183], v[20:23]
	v_mfma_f32_16x16x32_bf16 v[12:15], v[216:219], v[180:183], v[12:15]
	v_mfma_f32_16x16x32_bf16 v[12:15], v[212:215], v[176:179], v[12:15]
	v_mfma_f32_16x16x32_bf16 v[0:3], v[212:215], v[196:199], v[0:3]
	v_mfma_f32_16x16x32_bf16 v[0:3], v[216:219], v[200:203], v[0:3]
	v_mfma_f32_16x16x32_bf16 v[4:7], v[208:211], v[200:203], v[4:7]
	v_mfma_f32_16x16x32_bf16 v[4:7], v[204:207], v[196:199], v[4:7]
	s_setprio 0
	s_add_i32 s47, 0, 0x18000
	v_add_u32_e32 v140, s47, v187
	s_barrier
	ds_read_b128 v[128:131], v140
	ds_read_b128 v[132:135], v140 offset:1024
	ds_read_b128 v[136:139], v140 offset:2048
	ds_read_b128 v[140:143], v140 offset:3072
	s_add_u32 s24, s24, 0x100000
	s_addc_u32 s25, s25, 0
	s_mov_b32 m0, s40
	v_lshl_add_u64 v[204:205], s[24:25], 0, v[160:161]
	ds_read_b128 v[144:147], v194 offset:32768
	ds_read_b128 v[148:151], v194 offset:33792
	ds_read_b128 v[152:155], v194 offset:34816
	ds_read_b128 v[156:159], v194 offset:35840
	ds_read_b128 v[176:179], v194 offset:36864
	ds_read_b128 v[180:183], v194 offset:37888
	ds_read_b128 v[196:199], v194 offset:38912
	ds_read_b128 v[200:203], v194 offset:39936
	global_load_lds_dwordx4 v[204:205], off
	v_lshl_add_u64 v[204:205], s[24:25], 0, v[164:165]
	s_mov_b32 m0, s41
	s_nop 0
	global_load_lds_dwordx4 v[204:205], off
	s_waitcnt lgkmcnt(8)
	s_barrier
	s_waitcnt lgkmcnt(0)
	s_setprio 1
	s_waitcnt lgkmcnt(0)
	v_mfma_f32_16x16x32_bf16 v[124:127], v[128:131], v[144:147], v[124:127]
	v_mfma_f32_16x16x32_bf16 v[124:127], v[132:135], v[148:151], v[124:127]
	v_mfma_f32_16x16x32_bf16 v[120:123], v[140:143], v[148:151], v[120:123]
	v_mfma_f32_16x16x32_bf16 v[120:123], v[136:139], v[144:147], v[120:123]
	v_mfma_f32_16x16x32_bf16 v[104:107], v[136:139], v[152:155], v[104:107]
	v_mfma_f32_16x16x32_bf16 v[104:107], v[140:143], v[156:159], v[104:107]
	v_mfma_f32_16x16x32_bf16 v[112:115], v[132:135], v[156:159], v[112:115]
	v_mfma_f32_16x16x32_bf16 v[112:115], v[128:131], v[152:155], v[112:115]
	v_mfma_f32_16x16x32_bf16 v[92:95], v[128:131], v[176:179], v[92:95]
	v_mfma_f32_16x16x32_bf16 v[92:95], v[132:135], v[180:183], v[92:95]
	v_mfma_f32_16x16x32_bf16 v[88:91], v[140:143], v[180:183], v[88:91]
	v_mfma_f32_16x16x32_bf16 v[88:91], v[136:139], v[176:179], v[88:91]
	v_mfma_f32_16x16x32_bf16 v[72:75], v[136:139], v[196:199], v[72:75]
	v_mfma_f32_16x16x32_bf16 v[72:75], v[140:143], v[200:203], v[72:75]
	v_mfma_f32_16x16x32_bf16 v[76:79], v[132:135], v[200:203], v[76:79]
	v_mfma_f32_16x16x32_bf16 v[76:79], v[128:131], v[196:199], v[76:79]
	s_setprio 0
	s_barrier
	s_add_i32 s24, 0, 0x1c000
	s_add_i32 s25, s47, s34
	v_add_u32_e32 v216, s24, v187
	v_lshl_add_u64 v[184:185], v[184:185], 0, s[8:9]
	s_mov_b32 m0, s25
	ds_read_b128 v[204:207], v216
	ds_read_b128 v[208:211], v216 offset:1024
	ds_read_b128 v[212:215], v216 offset:2048
	ds_read_b128 v[216:219], v216 offset:3072
	global_load_lds_dwordx4 v[184:185], off
	v_lshl_add_u64 v[184:185], v[220:221], 0, s[8:9]
	s_add_i32 m0, s25, 0x2000
	s_nop 0
	global_load_lds_dwordx4 v[184:185], off
	s_barrier
	s_waitcnt lgkmcnt(0)
	s_setprio 1
	s_waitcnt lgkmcnt(0)
	v_mfma_f32_16x16x32_bf16 v[116:119], v[204:207], v[144:147], v[116:119]
	v_mfma_f32_16x16x32_bf16 v[116:119], v[208:211], v[148:151], v[116:119]
	v_mfma_f32_16x16x32_bf16 v[108:111], v[216:219], v[148:151], v[108:111]
	v_mfma_f32_16x16x32_bf16 v[108:111], v[212:215], v[144:147], v[108:111]
	v_mfma_f32_16x16x32_bf16 v[96:99], v[212:215], v[152:155], v[96:99]
	v_mfma_f32_16x16x32_bf16 v[96:99], v[216:219], v[156:159], v[96:99]
	v_mfma_f32_16x16x32_bf16 v[100:103], v[208:211], v[156:159], v[100:103]
	v_mfma_f32_16x16x32_bf16 v[100:103], v[204:207], v[152:155], v[100:103]
	v_mfma_f32_16x16x32_bf16 v[84:87], v[204:207], v[176:179], v[84:87]
	v_mfma_f32_16x16x32_bf16 v[84:87], v[208:211], v[180:183], v[84:87]
	v_mfma_f32_16x16x32_bf16 v[80:83], v[216:219], v[180:183], v[80:83]
	v_mfma_f32_16x16x32_bf16 v[80:83], v[212:215], v[176:179], v[80:83]
	v_mfma_f32_16x16x32_bf16 v[64:67], v[212:215], v[196:199], v[64:67]
	v_mfma_f32_16x16x32_bf16 v[64:67], v[216:219], v[200:203], v[64:67]
	v_mfma_f32_16x16x32_bf16 v[68:71], v[208:211], v[200:203], v[68:71]
	v_mfma_f32_16x16x32_bf16 v[68:71], v[204:207], v[196:199], v[68:71]
	s_setprio 0
	s_mov_b32 m0, s28
	v_lshl_add_u64 v[184:185], v[222:223], 0, s[8:9]
	s_barrier
	ds_read_b128 v[144:147], v194 offset:49152
	ds_read_b128 v[148:151], v194 offset:50176
	ds_read_b128 v[152:155], v194 offset:51200
	ds_read_b128 v[156:159], v194 offset:52224
	ds_read_b128 v[176:179], v194 offset:53248
	ds_read_b128 v[180:183], v194 offset:54272
	ds_read_b128 v[196:199], v194 offset:55296
	ds_read_b128 v[200:203], v194 offset:56320
	global_load_lds_dwordx4 v[184:185], off
	v_lshl_add_u64 v[184:185], v[224:225], 0, s[8:9]
	s_mov_b32 m0, s29
	s_nop 0
	global_load_lds_dwordx4 v[184:185], off
	s_barrier
; #define PG8_STAGE(bufoff, gbase, voff) do { _Pragma("unroll") for (int _i = 0; _i < 2; ++_i) \
;         __builtin_amdgcn_global_load_lds((const unsigned*)((const char*)(gbase) + (voff)[_i]), (LAS unsigned*)(lds + (bufoff) + ldsw + _i * 8192), 16, 0, 0); } while (0)
; #define PG8_MMA(ai, bj, At, Bt) do { __builtin_amdgcn_s_setprio(1); _Pragma("unroll") for (int m = 0; m < 4; ++m) _Pragma("unroll") for (int n = 0; n < 2; ++n) _Pragma("unroll") for (int k = 0; k < 2; ++k) \
;         acc[ai][bj][m][n] = __builtin_amdgcn_mfma_f32_16x16x32_bf16(Bt[n][k], At[m][k], acc[ai][bj][m][n], 0, 0, 0); __builtin_amdgcn_s_setprio(0); } while (0)
; #define PG8_WAIT_V(n) asm volatile("s_waitcnt vmcnt(" #n ")" ::: "memory")
; #define PG8_WAIT_L(n) asm volatile("s_waitcnt lgkmcnt(" #n ")" ::: "memory")
; #define PG8_BAR __builtin_amdgcn_s_barrier()
; #define PG8_SCHED __builtin_amdgcn_sched_barrier(0)
; template <class Epi, class Ptrs>
; __device__ __forceinline__ void gemm_phase(LAS unsigned char* lds, const int K, const StaticOrder& S, const Ptrs& P, const Epi& E) {
;     ...
;             PG8_BAR; PG8_WAIT_L(0); PG8_MMA(1, 0, At, B0); PG8_BAR; PG8_SCHED;
;             PG8_STAGE(PG8_SB(1, 1), b3 + hstep, voffB);
;             PG8_WAIT_V(6); PG8_BAR; PG8_MMA(1, 1, At, B1); PG8_BAR;
;     __device__ __forceinline__ void operator()(const f32x4 (&acc)[2][2][4][2], const Unit& u, int ui, int wr, int wc, int fr, int fq) const {
;         const int rl0 = wr * 64 + fr, col0 = u.pn * 256 + wc * 32 + 8 * fq;
;         u32x4 xv[2][4][2];
; #pragma unroll
;         for (int ai = 0; ai < 2; ++ai)
; #pragma unroll
;             for (int m = 0; m < 4; ++m)
; #pragma unroll
;                 for (int bj = 0; bj < 2; ++bj) xv[ai][m][bj] = *(const u32x4*)(xb + (size_t)(u.pm * 256 + rl0 + ai * 128 + m * 16) * DM + col0 + bj * 128);
; #pragma unroll
;         for (int ai = 0; ai < 2; ++ai)
; #pragma unroll
;             for (int m = 0; m < 4; ++m) { const int rl = rl0 + ai * 128 + m * 16; float* rowp = out + (size_t)(u.pm * 256 + rl) * DM + col0;
;                 const float r2 = tab[ui * 256 + rl];
	s_waitcnt lgkmcnt(0)
	s_setprio 1
	s_waitcnt lgkmcnt(0)
	v_mfma_f32_16x16x32_bf16 v[60:63], v[128:131], v[144:147], v[60:63]
	v_mfma_f32_16x16x32_bf16 v[60:63], v[132:135], v[148:151], v[60:63]
	v_mfma_f32_16x16x32_bf16 v[56:59], v[140:143], v[148:151], v[56:59]
	v_mfma_f32_16x16x32_bf16 v[56:59], v[136:139], v[144:147], v[56:59]
	v_mfma_f32_16x16x32_bf16 v[40:43], v[136:139], v[152:155], v[40:43]
	v_mfma_f32_16x16x32_bf16 v[40:43], v[140:143], v[156:159], v[40:43]
	v_mfma_f32_16x16x32_bf16 v[48:51], v[132:135], v[156:159], v[48:51]
	v_mfma_f32_16x16x32_bf16 v[48:51], v[128:131], v[152:155], v[48:51]
	v_mfma_f32_16x16x32_bf16 v[32:35], v[128:131], v[176:179], v[32:35]
	v_mfma_f32_16x16x32_bf16 v[32:35], v[132:135], v[180:183], v[32:35]
	v_mfma_f32_16x16x32_bf16 v[24:27], v[140:143], v[180:183], v[24:27]
	v_mfma_f32_16x16x32_bf16 v[24:27], v[136:139], v[176:179], v[24:27]
	v_mfma_f32_16x16x32_bf16 v[8:11], v[136:139], v[196:199], v[8:11]
	v_mfma_f32_16x16x32_bf16 v[8:11], v[140:143], v[200:203], v[8:11]
	v_mfma_f32_16x16x32_bf16 v[16:19], v[132:135], v[200:203], v[16:19]
	v_mfma_f32_16x16x32_bf16 v[16:19], v[128:131], v[196:199], v[16:19]
	s_setprio 0
	s_barrier
	s_add_u32 s22, s22, 0x100080
	s_addc_u32 s23, s23, 0
	s_add_i32 s24, s24, s34
	v_lshl_add_u64 v[128:129], s[22:23], 0, v[162:163]
	s_mov_b32 m0, s24
	s_nop 0
	global_load_lds_dwordx4 v[128:129], off
	v_lshl_add_u64 v[128:129], s[22:23], 0, v[166:167]
	s_add_i32 m0, s24, 0x2000
	s_nop 0
	global_load_lds_dwordx4 v[128:129], off
	s_waitcnt vmcnt(6)
	s_barrier
	s_setprio 1
	v_mfma_f32_16x16x32_bf16 v[52:55], v[204:207], v[144:147], v[52:55]
	v_mfma_f32_16x16x32_bf16 v[52:55], v[208:211], v[148:151], v[52:55]
	v_mfma_f32_16x16x32_bf16 v[44:47], v[216:219], v[148:151], v[44:47]
	v_mfma_f32_16x16x32_bf16 v[44:47], v[212:215], v[144:147], v[44:47]
	v_mfma_f32_16x16x32_bf16 v[28:31], v[212:215], v[152:155], v[28:31]
	v_mfma_f32_16x16x32_bf16 v[28:31], v[216:219], v[156:159], v[28:31]
	v_mfma_f32_16x16x32_bf16 v[36:39], v[208:211], v[156:159], v[36:39]
	v_mfma_f32_16x16x32_bf16 v[36:39], v[204:207], v[152:155], v[36:39]
	v_mfma_f32_16x16x32_bf16 v[20:23], v[204:207], v[176:179], v[20:23]
	v_mfma_f32_16x16x32_bf16 v[20:23], v[208:211], v[180:183], v[20:23]
	v_mfma_f32_16x16x32_bf16 v[12:15], v[216:219], v[180:183], v[12:15]
	v_mfma_f32_16x16x32_bf16 v[12:15], v[212:215], v[176:179], v[12:15]
	v_mfma_f32_16x16x32_bf16 v[0:3], v[212:215], v[196:199], v[0:3]
	v_mfma_f32_16x16x32_bf16 v[0:3], v[216:219], v[200:203], v[0:3]
	v_mfma_f32_16x16x32_bf16 v[4:7], v[208:211], v[200:203], v[4:7]
	v_mfma_f32_16x16x32_bf16 v[4:7], v[204:207], v[196:199], v[4:7]
	s_setprio 0
	s_add_i32 s46, s46, 2
	s_add_u32 s20, s20, 0x100
	s_addc_u32 s21, s21, 0
	s_add_u32 s11, s11, 0x100
	s_addc_u32 s13, s13, 0
	s_cmp_gt_u32 s46, 61
	s_barrier
	s_cbranch_scc0 .LBB0_522
	s_lshl_b32 s11, s18, 8
	v_lshl_or_b32 v128, s16, 8, v191
	v_add_u32_e32 v130, s11, v186
	v_ashrrev_i32_e32 v129, 31, v128
	v_ashrrev_i32_e32 v131, 31, v130
	v_lshl_add_u64 v[132:133], v[128:129], 1, s[6:7]
	v_lshlrev_b64 v[134:135], 11, v[130:131]
	v_lshl_add_u64 v[134:135], v[132:133], 0, v[134:135]
	global_load_dwordx4 v[198:201], v[134:135], off
	global_load_dwordx4 v[202:205], v[134:135], off offset:256
	v_or_b32_e32 v134, 16, v130
	v_ashrrev_i32_e32 v135, 31, v134
	v_lshlrev_b64 v[134:135], 11, v[134:135]
	v_lshl_add_u64 v[134:135], v[132:133], 0, v[134:135]
	global_load_dwordx4 v[206:209], v[134:135], off
	global_load_dwordx4 v[210:213], v[134:135], off offset:256
	v_or_b32_e32 v136, 32, v130
	v_ashrrev_i32_e32 v137, 31, v136
	v_or_b32_e32 v138, 48, v130
	v_add_u32_e32 v184, 0x80, v130
	v_add_u32_e32 v182, 0x90, v130
	v_add_u32_e32 v180, 0xa0, v130
	v_add_u32_e32 v178, 0xb0, v130
	v_lshlrev_b64 v[176:177], 2, v[128:129]
	v_lshlrev_b64 v[128:129], 12, v[130:131]
	v_lshlrev_b64 v[130:131], 11, v[136:137]
	v_lshl_add_u64 v[130:131], v[132:133], 0, v[130:131]
	global_load_dwordx4 v[214:217], v[130:131], off
	v_ashrrev_i32_e32 v139, 31, v138
	v_ashrrev_i32_e32 v185, 31, v184
	v_ashrrev_i32_e32 v183, 31, v182
	v_ashrrev_i32_e32 v181, 31, v180
	v_ashrrev_i32_e32 v179, 31, v178
	v_lshlrev_b64 v[134:135], 11, v[138:139]
	v_lshlrev_b64 v[136:137], 11, v[184:185]
	v_lshlrev_b64 v[138:139], 11, v[182:183]
	v_lshl_add_u32 v196, s45, 10, v192
	v_lshlrev_b64 v[140:141], 11, v[180:181]
	v_lshlrev_b64 v[142:143], 11, v[178:179]
	v_lshl_add_u64 v[128:129], s[26:27], 0, v[128:129]
	v_lshl_add_u64 v[134:135], v[132:133], 0, v[134:135]
	v_lshl_add_u64 v[136:137], v[132:133], 0, v[136:137]
	v_lshl_add_u64 v[138:139], v[132:133], 0, v[138:139]
	ds_read2_b32 v[230:231], v196 offset1:16
	v_lshl_add_u64 v[234:235], v[132:133], 0, v[140:141]
	v_lshl_add_u64 v[236:237], v[132:133], 0, v[142:143]
	v_lshl_add_u64 v[238:239], v[128:129], 0, v[176:177]
	global_load_dwordx4 v[218:221], v[130:131], off offset:256
	global_load_dwordx4 v[222:225], v[134:135], off
	global_load_dwordx4 v[226:229], v[134:135], off offset:256
	global_load_dwordx4 v[156:159], v[136:137], off
	global_load_dwordx4 v[152:155], v[136:137], off offset:256
	global_load_dwordx4 v[148:151], v[138:139], off
	global_load_dwordx4 v[144:147], v[138:139], off offset:256
	global_load_dwordx4 v[140:143], v[234:235], off
	s_nop 0
	global_load_dwordx4 v[136:139], v[234:235], off offset:256
	global_load_dwordx4 v[132:135], v[236:237], off
	global_load_dwordx4 v[128:131], v[236:237], off offset:256
	v_add_u32_e32 v232, s11, v188
	v_ashrrev_i32_e32 v233, 31, v232
	s_and_b64 vcc, exec, s[0:1]
	s_mov_b32 s16, s10
	s_mov_b32 s18, s12
	s_mov_b64 s[20:21], s[4:5]
	s_mov_b64 s[22:23], s[14:15]
	s_mov_b32 s45, s44
	s_waitcnt vmcnt(0)
; __device__ __forceinline__ float bf_lo(unsigned w) { return __uint_as_float(w << 16); }
; __device__ __forceinline__ float bf_hi(unsigned w) { return __uint_as_float(w & 0xffff0000u); }
;     __device__ __forceinline__ void operator()(const f32x4 (&acc)[2][2][4][2], const Unit& u, int ui, int wr, int wc, int fr, int fq) const {
;     ...
;         for (int ai = 0; ai < 2; ++ai)
; #pragma unroll
;             for (int m = 0; m < 4; ++m) { const int rl = rl0 + ai * 128 + m * 16; float* rowp = out + (size_t)(u.pm * 256 + rl) * DM + col0;
;                 const float r2 = tab[ui * 256 + rl];
; #pragma unroll
;                 for (int bj = 0; bj < 2; ++bj) { const u32x4 x = xv[ai][m][bj];
;                     const f32x4 x0 = {bf_lo(x.x), bf_hi(x.x), bf_lo(x.y), bf_hi(x.y)}, x1 = {bf_lo(x.z), bf_hi(x.z), bf_lo(x.w), bf_hi(x.w)};
;                     *(f32x4*)(rowp + bj * 128) = acc[ai][bj][m][0] * r2 + x0; *(f32x4*)(rowp + bj * 128 + 4) = acc[ai][bj][m][1] * r2 + x1; } }
	v_lshlrev_b32_e32 v234, 16, v198
	v_and_b32_e32 v235, 0xffff0000, v198
	v_lshlrev_b32_e32 v198, 16, v199
	v_and_b32_e32 v199, 0xffff0000, v199
	v_lshlrev_b32_e32 v242, 16, v204
	v_and_b32_e32 v243, 0xffff0000, v204
	v_lshlrev_b32_e32 v236, 16, v200
	v_and_b32_e32 v237, 0xffff0000, v200
	v_lshlrev_b32_e32 v200, 16, v201
	v_and_b32_e32 v201, 0xffff0000, v201
	v_lshlrev_b32_e32 v240, 16, v202
	v_and_b32_e32 v241, 0xffff0000, v202
	v_lshlrev_b32_e32 v202, 16, v203
	v_and_b32_e32 v203, 0xffff0000, v203
	v_lshlrev_b32_e32 v204, 16, v205
	v_and_b32_e32 v205, 0xffff0000, v205
	s_waitcnt lgkmcnt(0)
	v_pk_fma_f32 v[126:127], v[126:127], v[230:231], v[198:199] op_sel_hi:[1,0,1]
	v_pk_fma_f32 v[124:125], v[124:125], v[230:231], v[234:235] op_sel_hi:[1,0,1]
	v_pk_fma_f32 v[108:109], v[108:109], v[230:231], v[242:243] op_sel_hi:[1,0,1]
	v_pk_fma_f32 v[122:123], v[122:123], v[230:231], v[200:201] op_sel_hi:[1,0,1]
	v_pk_fma_f32 v[120:121], v[120:121], v[230:231], v[236:237] op_sel_hi:[1,0,1]
	v_pk_fma_f32 v[118:119], v[118:119], v[230:231], v[202:203] op_sel_hi:[1,0,1]
	v_pk_fma_f32 v[116:117], v[116:117], v[230:231], v[240:241] op_sel_hi:[1,0,1]
	v_pk_fma_f32 v[110:111], v[110:111], v[230:231], v[204:205] op_sel_hi:[1,0,1]
	global_store_dwordx4 v[238:239], v[124:127], off
	global_store_dwordx4 v[238:239], v[120:123], off offset:16
	global_store_dwordx4 v[238:239], v[116:119], off offset:512
	global_store_dwordx4 v[238:239], v[108:111], off offset:528
	v_mov_b32_e32 v122, v231
	v_lshlrev_b32_e32 v118, 16, v208
	v_lshlrev_b64 v[108:109], 12, v[232:233]
	v_lshl_add_u64 v[108:109], s[26:27], 0, v[108:109]
	v_lshl_add_u64 v[116:117], v[108:109], 0, v[176:177]
	v_lshlrev_b32_e32 v108, 16, v206
	v_and_b32_e32 v109, 0xffff0000, v206
	v_lshlrev_b32_e32 v110, 16, v207
	v_and_b32_e32 v111, 0xffff0000, v207
	v_pk_fma_f32 v[110:111], v[114:115], v[122:123], v[110:111] op_sel_hi:[1,0,1]
	v_pk_fma_f32 v[108:109], v[112:113], v[122:123], v[108:109] op_sel_hi:[1,0,1]
	global_store_dwordx4 v[116:117], v[108:111], off
	v_and_b32_e32 v119, 0xffff0000, v208
	v_lshlrev_b32_e32 v120, 16, v209
	v_lshlrev_b32_e32 v108, 16, v212
	v_and_b32_e32 v109, 0xffff0000, v212
	v_lshlrev_b32_e32 v110, 16, v213
	v_and_b32_e32 v111, 0xffff0000, v213
	v_pk_fma_f32 v[98:99], v[98:99], v[122:123], v[110:111] op_sel_hi:[1,0,1]
	v_pk_fma_f32 v[96:97], v[96:97], v[122:123], v[108:109] op_sel_hi:[1,0,1]
	v_and_b32_e32 v121, 0xffff0000, v209
	global_store_dwordx4 v[116:117], v[96:99], off offset:528
	ds_read2_b32 v[98:99], v196 offset0:32 offset1:48
	v_pk_fma_f32 v[106:107], v[106:107], v[122:123], v[120:121] op_sel_hi:[1,0,1]
	v_pk_fma_f32 v[104:105], v[104:105], v[122:123], v[118:119] op_sel_hi:[1,0,1]
	v_add_u32_e32 v96, s11, v189
	global_store_dwordx4 v[116:117], v[104:107], off offset:16
	v_ashrrev_i32_e32 v97, 31, v96
	v_lshlrev_b64 v[96:97], 12, v[96:97]
	v_lshlrev_b32_e32 v104, 16, v210
	v_and_b32_e32 v105, 0xffff0000, v210
	v_lshlrev_b32_e32 v106, 16, v211
	v_and_b32_e32 v107, 0xffff0000, v211
	v_pk_fma_f32 v[102:103], v[102:103], v[122:123], v[106:107] op_sel_hi:[1,0,1]
	v_pk_fma_f32 v[100:101], v[100:101], v[122:123], v[104:105] op_sel_hi:[1,0,1]
	global_store_dwordx4 v[116:117], v[100:103], off offset:512
	v_lshl_add_u64 v[96:97], s[26:27], 0, v[96:97]
	v_lshl_add_u64 v[96:97], v[96:97], 0, v[176:177]
	v_lshlrev_b32_e32 v100, 16, v214
	v_and_b32_e32 v101, 0xffff0000, v214
	v_lshlrev_b32_e32 v102, 16, v215
	v_and_b32_e32 v103, 0xffff0000, v215
	s_waitcnt lgkmcnt(0)
	v_pk_fma_f32 v[94:95], v[94:95], v[98:99], v[102:103] op_sel_hi:[1,0,1]
	v_pk_fma_f32 v[92:93], v[92:93], v[98:99], v[100:101] op_sel_hi:[1,0,1]
	global_store_dwordx4 v[96:97], v[92:95], off
	v_lshlrev_b32_e32 v104, 16, v216
	v_and_b32_e32 v105, 0xffff0000, v216
	v_lshlrev_b32_e32 v92, 16, v220
	v_and_b32_e32 v93, 0xffff0000, v220
	v_lshlrev_b32_e32 v94, 16, v221
	v_and_b32_e32 v95, 0xffff0000, v221
	v_lshlrev_b32_e32 v106, 16, v217
	v_and_b32_e32 v107, 0xffff0000, v217
	v_pk_fma_f32 v[82:83], v[82:83], v[98:99], v[94:95] op_sel_hi:[1,0,1]
	v_pk_fma_f32 v[80:81], v[80:81], v[98:99], v[92:93] op_sel_hi:[1,0,1]
	v_pk_fma_f32 v[90:91], v[90:91], v[98:99], v[106:107] op_sel_hi:[1,0,1]
	v_pk_fma_f32 v[88:89], v[88:89], v[98:99], v[104:105] op_sel_hi:[1,0,1]
	global_store_dwordx4 v[96:97], v[80:83], off offset:528
	global_store_dwordx4 v[96:97], v[88:91], off offset:16
	s_nop 0
	v_add_u32_e32 v80, s11, v190
	v_lshlrev_b32_e32 v88, 16, v218
	v_and_b32_e32 v89, 0xffff0000, v218
	v_lshlrev_b32_e32 v90, 16, v219
	v_and_b32_e32 v91, 0xffff0000, v219
	v_ashrrev_i32_e32 v81, 31, v80
	v_pk_fma_f32 v[86:87], v[86:87], v[98:99], v[90:91] op_sel_hi:[1,0,1]
	v_pk_fma_f32 v[84:85], v[84:85], v[98:99], v[88:89] op_sel_hi:[1,0,1]
	v_lshlrev_b64 v[80:81], 12, v[80:81]
	global_store_dwordx4 v[96:97], v[84:87], off offset:512
	v_lshl_add_u64 v[80:81], s[26:27], 0, v[80:81]
	v_lshlrev_b32_e32 v82, 16, v222
	v_and_b32_e32 v83, 0xffff0000, v222
	v_lshlrev_b32_e32 v84, 16, v223
	v_and_b32_e32 v85, 0xffff0000, v223
	v_mov_b32_e32 v90, v99
	v_lshl_add_u64 v[80:81], v[80:81], 0, v[176:177]
	v_pk_fma_f32 v[78:79], v[78:79], v[90:91], v[84:85] op_sel_hi:[1,0,1]
	v_pk_fma_f32 v[76:77], v[76:77], v[90:91], v[82:83] op_sel_hi:[1,0,1]
	global_store_dwordx4 v[80:81], v[76:79], off
	v_lshlrev_b32_e32 v86, 16, v224
	v_and_b32_e32 v87, 0xffff0000, v224
	v_lshlrev_b32_e32 v76, 16, v228
	v_and_b32_e32 v77, 0xffff0000, v228
	v_lshlrev_b32_e32 v78, 16, v229
	v_and_b32_e32 v79, 0xffff0000, v229
	v_pk_fma_f32 v[66:67], v[66:67], v[90:91], v[78:79] op_sel_hi:[1,0,1]
	v_pk_fma_f32 v[64:65], v[64:65], v[90:91], v[76:77] op_sel_hi:[1,0,1]
	v_lshlrev_b32_e32 v88, 16, v225
	v_and_b32_e32 v89, 0xffff0000, v225
	global_store_dwordx4 v[80:81], v[64:67], off offset:528
	ds_read2_b32 v[66:67], v196 offset0:128 offset1:144
	v_pk_fma_f32 v[74:75], v[74:75], v[90:91], v[88:89] op_sel_hi:[1,0,1]
	v_pk_fma_f32 v[72:73], v[72:73], v[90:91], v[86:87] op_sel_hi:[1,0,1]
	global_store_dwordx4 v[80:81], v[72:75], off offset:16
	v_lshlrev_b64 v[64:65], 12, v[184:185]
	v_lshl_add_u64 v[64:65], s[26:27], 0, v[64:65]
	v_lshlrev_b32_e32 v72, 16, v226
	v_and_b32_e32 v73, 0xffff0000, v226
	v_lshlrev_b32_e32 v74, 16, v227
	v_and_b32_e32 v75, 0xffff0000, v227
	v_pk_fma_f32 v[70:71], v[70:71], v[90:91], v[74:75] op_sel_hi:[1,0,1]
	v_pk_fma_f32 v[68:69], v[68:69], v[90:91], v[72:73] op_sel_hi:[1,0,1]
	global_store_dwordx4 v[80:81], v[68:71], off offset:512
	v_lshl_add_u64 v[64:65], v[64:65], 0, v[176:177]
	v_lshlrev_b32_e32 v72, 16, v158
	v_lshlrev_b32_e32 v68, 16, v156
	v_and_b32_e32 v69, 0xffff0000, v156
	v_lshlrev_b32_e32 v70, 16, v157
	v_and_b32_e32 v71, 0xffff0000, v157
	v_and_b32_e32 v73, 0xffff0000, v158
	v_lshlrev_b32_e32 v74, 16, v159
	v_and_b32_e32 v75, 0xffff0000, v159
	s_waitcnt lgkmcnt(0)
; __device__ __forceinline__ float bf_lo(unsigned w) { return __uint_as_float(w << 16); }
; __device__ __forceinline__ float bf_hi(unsigned w) { return __uint_as_float(w & 0xffff0000u); }
; #define PG8_WAIT_V(n) asm volatile("s_waitcnt vmcnt(" #n ")" ::: "memory")
; #define PG8_BAR __builtin_amdgcn_s_barrier()
; template <class Epi, class Ptrs>
; __device__ __forceinline__ void gemm_phase(LAS unsigned char* lds, const int K, const StaticOrder& S, const Ptrs& P, const Epi& E) {
;     ...
;         cur = nxt; cA = nA; cB = nB; ++ui;
;     }
;     PG8_WAIT_V(0);
;     if (wr == 0) PG8_BAR;
;     PG8_BAR;
;     __device__ __forceinline__ void operator()(const f32x4 (&acc)[2][2][4][2], const Unit& u, int ui, int wr, int wc, int fr, int fq) const {
;     ...
;         for (int ai = 0; ai < 2; ++ai)
; #pragma unroll
;             for (int m = 0; m < 4; ++m) { const int rl = rl0 + ai * 128 + m * 16; float* rowp = out + (size_t)(u.pm * 256 + rl) * DM + col0;
;                 const float r2 = tab[ui * 256 + rl];
; #pragma unroll
;                 for (int bj = 0; bj < 2; ++bj) { const u32x4 x = xv[ai][m][bj];
;                     const f32x4 x0 = {bf_lo(x.x), bf_hi(x.x), bf_lo(x.y), bf_hi(x.y)}, x1 = {bf_lo(x.z), bf_hi(x.z), bf_lo(x.w), bf_hi(x.w)};
;                     *(f32x4*)(rowp + bj * 128) = acc[ai][bj][m][0] * r2 + x0; *(f32x4*)(rowp + bj * 128 + 4) = acc[ai][bj][m][1] * r2 + x1; } }
	v_pk_fma_f32 v[62:63], v[62:63], v[66:67], v[70:71] op_sel_hi:[1,0,1]
	v_pk_fma_f32 v[60:61], v[60:61], v[66:67], v[68:69] op_sel_hi:[1,0,1]
	global_store_dwordx4 v[64:65], v[60:63], off
	v_pk_fma_f32 v[58:59], v[58:59], v[66:67], v[74:75] op_sel_hi:[1,0,1]
	v_pk_fma_f32 v[56:57], v[56:57], v[66:67], v[72:73] op_sel_hi:[1,0,1]
	v_lshlrev_b32_e32 v60, 16, v154
	v_and_b32_e32 v61, 0xffff0000, v154
	v_lshlrev_b32_e32 v62, 16, v155
	v_and_b32_e32 v63, 0xffff0000, v155
	global_store_dwordx4 v[64:65], v[56:59], off offset:16
	v_pk_fma_f32 v[46:47], v[46:47], v[66:67], v[62:63] op_sel_hi:[1,0,1]
	v_pk_fma_f32 v[44:45], v[44:45], v[66:67], v[60:61] op_sel_hi:[1,0,1]
	v_lshlrev_b32_e32 v56, 16, v152
	v_and_b32_e32 v57, 0xffff0000, v152
	v_lshlrev_b32_e32 v58, 16, v153
	v_and_b32_e32 v59, 0xffff0000, v153
	v_pk_fma_f32 v[54:55], v[54:55], v[66:67], v[58:59] op_sel_hi:[1,0,1]
	v_pk_fma_f32 v[52:53], v[52:53], v[66:67], v[56:57] op_sel_hi:[1,0,1]
	global_store_dwordx4 v[64:65], v[44:47], off offset:528
	global_store_dwordx4 v[64:65], v[52:55], off offset:512
	v_lshlrev_b32_e32 v56, 16, v151
	v_lshlrev_b64 v[44:45], 12, v[182:183]
	v_lshl_add_u64 v[44:45], s[26:27], 0, v[44:45]
	v_lshlrev_b32_e32 v54, 16, v150
	v_and_b32_e32 v55, 0xffff0000, v150
	v_and_b32_e32 v57, 0xffff0000, v151
	v_mov_b32_e32 v58, v67
	v_lshl_add_u64 v[52:53], v[44:45], 0, v[176:177]
	v_pk_fma_f32 v[42:43], v[42:43], v[58:59], v[56:57] op_sel_hi:[1,0,1]
	v_pk_fma_f32 v[40:41], v[40:41], v[58:59], v[54:55] op_sel_hi:[1,0,1]
	v_lshlrev_b32_e32 v44, 16, v148
	v_and_b32_e32 v45, 0xffff0000, v148
	v_lshlrev_b32_e32 v46, 16, v149
	v_and_b32_e32 v47, 0xffff0000, v149
	global_store_dwordx4 v[52:53], v[40:43], off offset:16
	v_pk_fma_f32 v[46:47], v[50:51], v[58:59], v[46:47] op_sel_hi:[1,0,1]
	v_pk_fma_f32 v[44:45], v[48:49], v[58:59], v[44:45] op_sel_hi:[1,0,1]
	v_lshlrev_b32_e32 v40, 16, v144
	v_and_b32_e32 v41, 0xffff0000, v144
	v_lshlrev_b32_e32 v42, 16, v145
	v_and_b32_e32 v43, 0xffff0000, v145
	v_pk_fma_f32 v[38:39], v[38:39], v[58:59], v[42:43] op_sel_hi:[1,0,1]
	v_pk_fma_f32 v[36:37], v[36:37], v[58:59], v[40:41] op_sel_hi:[1,0,1]
	global_store_dwordx4 v[52:53], v[44:47], off
	global_store_dwordx4 v[52:53], v[36:39], off offset:512
	ds_read2_b32 v[38:39], v196 offset0:160 offset1:176
	v_lshlrev_b32_e32 v44, 16, v146
	v_and_b32_e32 v45, 0xffff0000, v146
	v_lshlrev_b32_e32 v46, 16, v147
	v_and_b32_e32 v47, 0xffff0000, v147
	v_pk_fma_f32 v[30:31], v[30:31], v[58:59], v[46:47] op_sel_hi:[1,0,1]
	v_pk_fma_f32 v[28:29], v[28:29], v[58:59], v[44:45] op_sel_hi:[1,0,1]
	global_store_dwordx4 v[52:53], v[28:31], off offset:528
	v_lshlrev_b32_e32 v40, 16, v142
	v_and_b32_e32 v41, 0xffff0000, v142
	v_lshlrev_b64 v[28:29], 12, v[180:181]
	v_lshl_add_u64 v[28:29], s[26:27], 0, v[28:29]
	v_lshl_add_u64 v[36:37], v[28:29], 0, v[176:177]
	v_lshlrev_b32_e32 v28, 16, v140
	v_and_b32_e32 v29, 0xffff0000, v140
	v_lshlrev_b32_e32 v30, 16, v141
	v_and_b32_e32 v31, 0xffff0000, v141
	s_waitcnt lgkmcnt(0)
	v_pk_fma_f32 v[30:31], v[34:35], v[38:39], v[30:31] op_sel_hi:[1,0,1]
	v_pk_fma_f32 v[28:29], v[32:33], v[38:39], v[28:29] op_sel_hi:[1,0,1]
	v_lshlrev_b32_e32 v42, 16, v143
	v_and_b32_e32 v43, 0xffff0000, v143
	global_store_dwordx4 v[36:37], v[28:31], off
	v_pk_fma_f32 v[26:27], v[26:27], v[38:39], v[42:43] op_sel_hi:[1,0,1]
	v_pk_fma_f32 v[24:25], v[24:25], v[38:39], v[40:41] op_sel_hi:[1,0,1]
	v_lshlrev_b32_e32 v28, 16, v138
	v_and_b32_e32 v29, 0xffff0000, v138
	v_lshlrev_b32_e32 v30, 16, v139
	v_and_b32_e32 v31, 0xffff0000, v139
	v_pk_fma_f32 v[14:15], v[14:15], v[38:39], v[30:31] op_sel_hi:[1,0,1]
	v_pk_fma_f32 v[12:13], v[12:13], v[38:39], v[28:29] op_sel_hi:[1,0,1]
	global_store_dwordx4 v[36:37], v[24:27], off offset:16
	global_store_dwordx4 v[36:37], v[12:15], off offset:528
	s_nop 0
	v_lshlrev_b32_e32 v24, 16, v136
	v_and_b32_e32 v25, 0xffff0000, v136
	v_lshlrev_b32_e32 v26, 16, v137
	v_and_b32_e32 v27, 0xffff0000, v137
	v_lshlrev_b64 v[12:13], 12, v[178:179]
	v_pk_fma_f32 v[22:23], v[22:23], v[38:39], v[26:27] op_sel_hi:[1,0,1]
	v_pk_fma_f32 v[20:21], v[20:21], v[38:39], v[24:25] op_sel_hi:[1,0,1]
	v_lshl_add_u64 v[12:13], s[26:27], 0, v[12:13]
	global_store_dwordx4 v[36:37], v[20:23], off offset:512
	v_lshlrev_b32_e32 v14, 16, v133
	v_and_b32_e32 v15, 0xffff0000, v133
	v_lshl_add_u64 v[20:21], v[12:13], 0, v[176:177]
	v_lshlrev_b32_e32 v12, 16, v132
	v_and_b32_e32 v13, 0xffff0000, v132
	v_lshlrev_b32_e32 v22, 16, v134
	v_and_b32_e32 v23, 0xffff0000, v134
	v_lshlrev_b32_e32 v24, 16, v135
	v_and_b32_e32 v25, 0xffff0000, v135
	v_mov_b32_e32 v26, v39
	v_pk_fma_f32 v[14:15], v[18:19], v[26:27], v[14:15] op_sel_hi:[1,0,1]
	v_pk_fma_f32 v[12:13], v[16:17], v[26:27], v[12:13] op_sel_hi:[1,0,1]
	v_pk_fma_f32 v[10:11], v[10:11], v[26:27], v[24:25] op_sel_hi:[1,0,1]
	v_pk_fma_f32 v[8:9], v[8:9], v[26:27], v[22:23] op_sel_hi:[1,0,1]
	global_store_dwordx4 v[20:21], v[12:15], off
	global_store_dwordx4 v[20:21], v[8:11], off offset:16
	s_nop 0
	v_lshlrev_b32_e32 v12, 16, v130
	v_lshlrev_b32_e32 v8, 16, v128
	v_and_b32_e32 v9, 0xffff0000, v128
	v_lshlrev_b32_e32 v10, 16, v129
	v_and_b32_e32 v11, 0xffff0000, v129
	v_and_b32_e32 v13, 0xffff0000, v130
	v_lshlrev_b32_e32 v14, 16, v131
	v_and_b32_e32 v15, 0xffff0000, v131
	v_pk_fma_f32 v[6:7], v[6:7], v[26:27], v[10:11] op_sel_hi:[1,0,1]
	v_pk_fma_f32 v[4:5], v[4:5], v[26:27], v[8:9] op_sel_hi:[1,0,1]
	v_pk_fma_f32 v[2:3], v[2:3], v[26:27], v[14:15] op_sel_hi:[1,0,1]
	v_pk_fma_f32 v[0:1], v[0:1], v[26:27], v[12:13] op_sel_hi:[1,0,1]
	global_store_dwordx4 v[20:21], v[4:7], off offset:512
	global_store_dwordx4 v[20:21], v[0:3], off offset:528
	s_cbranch_vccz .LBB0_517
	s_waitcnt vmcnt(0)
	s_cmpk_gt_u32 s33, 0xff
	s_cbranch_scc1 .LBB0_526
	s_barrier
